# one static priority raise for waves 4-7 at kernel entry, all 112 per-segment s_setprio toggles in the GEMM loops removed
# baseline (speedup 1.0000x reference)
_Z10fwd_kernel6Params:
	s_add_u32 s10, s0, 0xa0
	v_writelane_b32 v255, s2, 0
	s_load_dwordx2 s[28:29], s[0:1], 0xa0
	s_load_dword s2, s[0:1], 0xa8
	s_addc_u32 s11, s1, 0
	v_and_b32_e32 v147, 0x3ff, v0
	s_nop 0
	v_readfirstlane_b32 s3, v147
	s_nop 0
	s_cmp_lt_u32 s3, 0x100
	s_cbranch_scc1 .Lsprio_skip
	s_setprio 1
.Lsprio_skip:
	v_cmp_eq_u32_e32 vcc, 0, v147
	s_and_saveexec_b64 s[4:5], vcc
	s_cbranch_execz .LBB0_3
	s_add_i32 s3, 0, 0x23f00
	v_mov_b32_e32 v1, 0
	v_mov_b32_e32 v2, s3
	s_add_i32 s3, 0, 0x23f04
	s_mov_b64 s[6:7], exec
	ds_write_b32 v2, v1
	v_mov_b32_e32 v2, s3
	ds_write_b32 v2, v1
	v_mbcnt_lo_u32_b32 v1, s6, 0
	v_mbcnt_hi_u32_b32 v1, s7, v1
	v_cmp_eq_u32_e32 vcc, 0, v1
	s_getreg_b32 s3, hwreg(HW_REG_XCC_ID, 0, 4)
	s_and_b64 s[8:9], exec, vcc
	s_mov_b64 exec, s[8:9]
	s_cbranch_execz .LBB0_3
	s_load_dwordx2 s[8:9], s[0:1], 0x98
	s_lshl_b32 s3, s3, 8
	s_and_b32 s3, s3, 0xf00
	v_mov_b32_e32 v1, 0x4000
	s_waitcnt lgkmcnt(0)
	s_add_u32 s8, s8, s3
	s_addc_u32 s9, s9, 0
	s_bcnt1_i32_b64 s3, s[6:7]
	v_mov_b32_e32 v2, s3
	global_atomic_add v3, v1, v2, s[8:9] offset:1024 sc0
	s_waitcnt vmcnt(0)
	v_readfirstlane_b32 s6, v3
	s_getreg_b32 s7, hwreg(HW_REG_XCC_ID, 0, 4)
	s_and_b32 s7, s7, 7
	s_nop 0
	s_bfe_u32 s3, s6, 0x10002
	s_and_b32 s9, s6, 3
	s_lshl_b32 s9, s9, 1
	s_or_b32 s3, s3, s9
	s_lshl_b32 s9, s7, 3
	s_or_b32 s3, s3, s9
	s_lshr_b32 s9, s6, 3
	s_lshl_b32 s9, s9, 6
	s_or_b32 s3, s3, s9
	v_mov_b32_e32 v1, 0x23f08
	v_mov_b32_e32 v2, s3
	ds_write_b32 v1, v2

.LBB0_345:
	s_add_u32 s42, s56, 0xfffc0080
	s_addc_u32 s43, s57, -1
	s_add_i32 s59, 0, 0x10000
	s_cmp_eq_u32 s58, 12
	s_cselect_b32 s55, s17, s43
	s_cselect_b32 s54, s19, s42
	v_add_u32_e32 v138, s59, v141
	s_cselect_b32 s43, s15, s53
	s_cselect_b32 s42, s50, s51
	s_add_i32 s62, 0, 0x14000
	ds_read_b128 v[154:157], v138
	ds_read_b128 v[158:161], v138 offset:1024
	ds_read_b128 v[162:165], v138 offset:2048
	ds_read_b128 v[166:169], v138 offset:3072
	v_add_u32_e32 v138, s62, v141
	ds_read_b128 v[170:173], v138
	ds_read_b128 v[174:177], v138 offset:1024
	ds_read_b128 v[178:181], v138 offset:2048
	ds_read_b128 v[204:207], v138 offset:3072
	v_lshl_add_u64 v[138:139], s[56:57], 0, v[134:135]
	s_add_i32 m0, s38, 0xc000
	ds_read_b128 v[208:211], v143
	ds_read_b128 v[212:215], v143 offset:1024
	ds_read_b128 v[216:219], v143 offset:2048
	ds_read_b128 v[220:223], v143 offset:3072
	ds_read_b128 v[224:227], v143 offset:4096
	ds_read_b128 v[228:231], v143 offset:5120
	ds_read_b128 v[232:235], v143 offset:6144
	ds_read_b128 v[236:239], v143 offset:7168
	global_load_lds_dwordx4 v[138:139], off
	v_lshl_add_u64 v[138:139], s[56:57], 0, v[136:137]
	s_add_i32 m0, s38, 0xe000
	s_nop 0
	global_load_lds_dwordx4 v[138:139], off
	s_waitcnt vmcnt(8)
	s_waitcnt lgkmcnt(0)
	s_barrier
	s_waitcnt lgkmcnt(0)
	v_mfma_f32_16x16x32_bf16 v[124:127], v[154:157], v[208:211], v[124:127]
	v_mfma_f32_16x16x32_bf16 v[116:119], v[162:165], v[208:211], v[116:119]
	v_mfma_f32_16x16x32_bf16 v[108:111], v[154:157], v[216:219], v[108:111]
	v_mfma_f32_16x16x32_bf16 v[100:103], v[162:165], v[216:219], v[100:103]
	v_mfma_f32_16x16x32_bf16 v[92:95], v[154:157], v[224:227], v[92:95]
	v_mfma_f32_16x16x32_bf16 v[84:87], v[162:165], v[224:227], v[84:87]
	v_mfma_f32_16x16x32_bf16 v[76:79], v[154:157], v[232:235], v[76:79]
	v_mfma_f32_16x16x32_bf16 v[68:71], v[162:165], v[232:235], v[68:71]
	v_mfma_f32_16x16x32_bf16 v[124:127], v[158:161], v[212:215], v[124:127]
	v_mfma_f32_16x16x32_bf16 v[116:119], v[166:169], v[212:215], v[116:119]
	v_mfma_f32_16x16x32_bf16 v[108:111], v[158:161], v[220:223], v[108:111]
	v_mfma_f32_16x16x32_bf16 v[100:103], v[166:169], v[220:223], v[100:103]
	v_mfma_f32_16x16x32_bf16 v[92:95], v[158:161], v[228:231], v[92:95]
	v_mfma_f32_16x16x32_bf16 v[84:87], v[166:169], v[228:231], v[84:87]
	v_mfma_f32_16x16x32_bf16 v[76:79], v[158:161], v[236:239], v[76:79]
	v_mfma_f32_16x16x32_bf16 v[68:71], v[166:169], v[236:239], v[68:71]
	v_mfma_f32_16x16x32_bf16 v[120:123], v[170:173], v[208:211], v[120:123]
	v_mfma_f32_16x16x32_bf16 v[112:115], v[178:181], v[208:211], v[112:115]
	v_mfma_f32_16x16x32_bf16 v[104:107], v[170:173], v[216:219], v[104:107]
	v_mfma_f32_16x16x32_bf16 v[96:99], v[178:181], v[216:219], v[96:99]
	v_mfma_f32_16x16x32_bf16 v[88:91], v[170:173], v[224:227], v[88:91]
	v_mfma_f32_16x16x32_bf16 v[80:83], v[178:181], v[224:227], v[80:83]
	v_mfma_f32_16x16x32_bf16 v[72:75], v[170:173], v[232:235], v[72:75]
	v_mfma_f32_16x16x32_bf16 v[64:67], v[178:181], v[232:235], v[64:67]
	v_mfma_f32_16x16x32_bf16 v[120:123], v[174:177], v[212:215], v[120:123]
	v_mfma_f32_16x16x32_bf16 v[112:115], v[204:207], v[212:215], v[112:115]
	v_mfma_f32_16x16x32_bf16 v[104:107], v[174:177], v[220:223], v[104:107]
	v_mfma_f32_16x16x32_bf16 v[96:99], v[204:207], v[220:223], v[96:99]
	v_mfma_f32_16x16x32_bf16 v[88:91], v[174:177], v[228:231], v[88:91]
	v_mfma_f32_16x16x32_bf16 v[80:83], v[204:207], v[228:231], v[80:83]
	v_mfma_f32_16x16x32_bf16 v[72:75], v[174:177], v[236:239], v[72:75]
	v_mfma_f32_16x16x32_bf16 v[64:67], v[204:207], v[236:239], v[64:67]
	s_barrier
	s_add_i32 s59, s59, s36
	v_lshl_add_u64 v[138:139], s[42:43], 0, v[144:145]
	s_mov_b32 m0, s59
	ds_read_b128 v[208:211], v143 offset:16384
	ds_read_b128 v[212:215], v143 offset:17408
	ds_read_b128 v[216:219], v143 offset:18432
	ds_read_b128 v[220:223], v143 offset:19456
	ds_read_b128 v[224:227], v143 offset:20480
	ds_read_b128 v[228:231], v143 offset:21504
	ds_read_b128 v[232:235], v143 offset:22528
	ds_read_b128 v[236:239], v143 offset:23552
	global_load_lds_dwordx4 v[138:139], off
	s_add_i32 m0, s59, 0x2000
	s_add_u32 s60, s42, 0x40000
	v_lshl_add_u64 v[240:241], s[42:43], 0, v[128:129]
	s_addc_u32 s61, s43, 0
	s_add_i32 s59, s62, s36
	global_load_lds_dwordx4 v[240:241], off
	v_lshl_add_u64 v[242:243], s[60:61], 0, v[144:145]
	s_mov_b32 m0, s59
	v_lshl_add_u64 v[244:245], s[54:55], 0, v[130:131]
	global_load_lds_dwordx4 v[242:243], off
	v_lshl_add_u64 v[242:243], s[60:61], 0, v[128:129]
	s_add_i32 m0, s59, 0x2000
	s_nop 0
	global_load_lds_dwordx4 v[242:243], off
	v_lshl_add_u64 v[242:243], s[54:55], 0, v[132:133]
	s_mov_b32 m0, s38
	s_nop 0
	global_load_lds_dwordx4 v[242:243], off
	s_mov_b32 m0, s40
	s_nop 0
	global_load_lds_dwordx4 v[244:245], off
	s_waitcnt vmcnt(8)
	s_waitcnt lgkmcnt(0)
	s_barrier
	s_waitcnt lgkmcnt(0)
	v_mfma_f32_16x16x32_bf16 v[60:63], v[154:157], v[208:211], v[60:63]
	v_mfma_f32_16x16x32_bf16 v[52:55], v[162:165], v[208:211], v[52:55]
	v_mfma_f32_16x16x32_bf16 v[44:47], v[154:157], v[216:219], v[44:47]
	v_mfma_f32_16x16x32_bf16 v[36:39], v[162:165], v[216:219], v[36:39]
	v_mfma_f32_16x16x32_bf16 v[28:31], v[154:157], v[224:227], v[28:31]
	v_mfma_f32_16x16x32_bf16 v[20:23], v[162:165], v[224:227], v[20:23]
	v_mfma_f32_16x16x32_bf16 v[12:15], v[154:157], v[232:235], v[12:15]
	v_mfma_f32_16x16x32_bf16 v[4:7], v[162:165], v[232:235], v[4:7]
	v_mfma_f32_16x16x32_bf16 v[60:63], v[158:161], v[212:215], v[60:63]
	v_mfma_f32_16x16x32_bf16 v[52:55], v[166:169], v[212:215], v[52:55]
	v_mfma_f32_16x16x32_bf16 v[44:47], v[158:161], v[220:223], v[44:47]
	v_mfma_f32_16x16x32_bf16 v[36:39], v[166:169], v[220:223], v[36:39]
	v_mfma_f32_16x16x32_bf16 v[28:31], v[158:161], v[228:231], v[28:31]
	v_mfma_f32_16x16x32_bf16 v[20:23], v[166:169], v[228:231], v[20:23]
	v_mfma_f32_16x16x32_bf16 v[12:15], v[158:161], v[236:239], v[12:15]
	v_mfma_f32_16x16x32_bf16 v[4:7], v[166:169], v[236:239], v[4:7]
	v_mfma_f32_16x16x32_bf16 v[56:59], v[170:173], v[208:211], v[56:59]
	v_mfma_f32_16x16x32_bf16 v[48:51], v[178:181], v[208:211], v[48:51]
	v_mfma_f32_16x16x32_bf16 v[40:43], v[170:173], v[216:219], v[40:43]
	v_mfma_f32_16x16x32_bf16 v[32:35], v[178:181], v[216:219], v[32:35]
	v_mfma_f32_16x16x32_bf16 v[24:27], v[170:173], v[224:227], v[24:27]
	v_mfma_f32_16x16x32_bf16 v[16:19], v[178:181], v[224:227], v[16:19]
	v_mfma_f32_16x16x32_bf16 v[8:11], v[170:173], v[232:235], v[8:11]
	v_mfma_f32_16x16x32_bf16 v[0:3], v[178:181], v[232:235], v[0:3]
	v_mfma_f32_16x16x32_bf16 v[56:59], v[174:177], v[212:215], v[56:59]
	v_mfma_f32_16x16x32_bf16 v[48:51], v[204:207], v[212:215], v[48:51]
	v_mfma_f32_16x16x32_bf16 v[40:43], v[174:177], v[220:223], v[40:43]
	v_mfma_f32_16x16x32_bf16 v[32:35], v[204:207], v[220:223], v[32:35]
	v_mfma_f32_16x16x32_bf16 v[24:27], v[174:177], v[228:231], v[24:27]
	v_mfma_f32_16x16x32_bf16 v[16:19], v[204:207], v[228:231], v[16:19]
	v_mfma_f32_16x16x32_bf16 v[8:11], v[174:177], v[236:239], v[8:11]
	v_mfma_f32_16x16x32_bf16 v[0:3], v[204:207], v[236:239], v[0:3]
	s_barrier
	s_add_i32 s59, 0, 0x18000
	s_add_i32 s60, 0, 0x1c000
	v_add_u32_e32 v166, s59, v141
	v_add_u32_e32 v190, s60, v141
	ds_read_b128 v[154:157], v166
	ds_read_b128 v[158:161], v166 offset:1024
	ds_read_b128 v[162:165], v166 offset:2048
	ds_read_b128 v[166:169], v166 offset:3072
	ds_read_b128 v[170:173], v190
	ds_read_b128 v[174:177], v190 offset:1024
	ds_read_b128 v[178:181], v190 offset:2048
	ds_read_b128 v[204:207], v190 offset:3072
	s_add_u32 s54, s54, 0x40000
	s_addc_u32 s55, s55, 0
	s_mov_b32 m0, s41
	v_lshl_add_u64 v[246:247], s[54:55], 0, v[132:133]
	ds_read_b128 v[208:211], v143 offset:32768
	ds_read_b128 v[212:215], v143 offset:33792
	ds_read_b128 v[216:219], v143 offset:34816
	ds_read_b128 v[220:223], v143 offset:35840
	ds_read_b128 v[224:227], v143 offset:36864
	ds_read_b128 v[228:231], v143 offset:37888
	ds_read_b128 v[232:235], v143 offset:38912
	ds_read_b128 v[236:239], v143 offset:39936
	global_load_lds_dwordx4 v[246:247], off
	v_lshl_add_u64 v[246:247], s[54:55], 0, v[130:131]
	s_mov_b32 m0, s44
	s_nop 0
	global_load_lds_dwordx4 v[246:247], off
	s_waitcnt vmcnt(8)
	s_waitcnt lgkmcnt(0)
	s_barrier
	s_waitcnt lgkmcnt(0)
	v_mfma_f32_16x16x32_bf16 v[124:127], v[154:157], v[208:211], v[124:127]
	v_mfma_f32_16x16x32_bf16 v[116:119], v[162:165], v[208:211], v[116:119]
	v_mfma_f32_16x16x32_bf16 v[108:111], v[154:157], v[216:219], v[108:111]
	v_mfma_f32_16x16x32_bf16 v[100:103], v[162:165], v[216:219], v[100:103]
	v_mfma_f32_16x16x32_bf16 v[92:95], v[154:157], v[224:227], v[92:95]
	v_mfma_f32_16x16x32_bf16 v[84:87], v[162:165], v[224:227], v[84:87]
	v_mfma_f32_16x16x32_bf16 v[76:79], v[154:157], v[232:235], v[76:79]
	v_mfma_f32_16x16x32_bf16 v[68:71], v[162:165], v[232:235], v[68:71]
	v_mfma_f32_16x16x32_bf16 v[124:127], v[158:161], v[212:215], v[124:127]
	v_mfma_f32_16x16x32_bf16 v[116:119], v[166:169], v[212:215], v[116:119]
	v_mfma_f32_16x16x32_bf16 v[108:111], v[158:161], v[220:223], v[108:111]
	v_mfma_f32_16x16x32_bf16 v[100:103], v[166:169], v[220:223], v[100:103]
	v_mfma_f32_16x16x32_bf16 v[92:95], v[158:161], v[228:231], v[92:95]
	v_mfma_f32_16x16x32_bf16 v[84:87], v[166:169], v[228:231], v[84:87]
	v_mfma_f32_16x16x32_bf16 v[76:79], v[158:161], v[236:239], v[76:79]
	v_mfma_f32_16x16x32_bf16 v[68:71], v[166:169], v[236:239], v[68:71]
	v_mfma_f32_16x16x32_bf16 v[120:123], v[170:173], v[208:211], v[120:123]
	v_mfma_f32_16x16x32_bf16 v[112:115], v[178:181], v[208:211], v[112:115]
	v_mfma_f32_16x16x32_bf16 v[104:107], v[170:173], v[216:219], v[104:107]
	v_mfma_f32_16x16x32_bf16 v[96:99], v[178:181], v[216:219], v[96:99]
	v_mfma_f32_16x16x32_bf16 v[88:91], v[170:173], v[224:227], v[88:91]
	v_mfma_f32_16x16x32_bf16 v[80:83], v[178:181], v[224:227], v[80:83]
	v_mfma_f32_16x16x32_bf16 v[72:75], v[170:173], v[232:235], v[72:75]
	v_mfma_f32_16x16x32_bf16 v[64:67], v[178:181], v[232:235], v[64:67]
	v_mfma_f32_16x16x32_bf16 v[120:123], v[174:177], v[212:215], v[120:123]
	v_mfma_f32_16x16x32_bf16 v[112:115], v[204:207], v[212:215], v[112:115]
	v_mfma_f32_16x16x32_bf16 v[104:107], v[174:177], v[220:223], v[104:107]
	v_mfma_f32_16x16x32_bf16 v[96:99], v[204:207], v[220:223], v[96:99]
	v_mfma_f32_16x16x32_bf16 v[88:91], v[174:177], v[228:231], v[88:91]
	v_mfma_f32_16x16x32_bf16 v[80:83], v[204:207], v[228:231], v[80:83]
	v_mfma_f32_16x16x32_bf16 v[72:75], v[174:177], v[236:239], v[72:75]
	v_mfma_f32_16x16x32_bf16 v[64:67], v[204:207], v[236:239], v[64:67]
	s_barrier
	s_add_i32 s54, s59, s36
	v_lshl_add_u64 v[138:139], v[138:139], 0, s[48:49]
	s_mov_b32 m0, s54
	ds_read_b128 v[208:211], v143 offset:49152
	ds_read_b128 v[212:215], v143 offset:50176
	ds_read_b128 v[216:219], v143 offset:51200
	ds_read_b128 v[220:223], v143 offset:52224
	ds_read_b128 v[224:227], v143 offset:53248
	ds_read_b128 v[228:231], v143 offset:54272
	ds_read_b128 v[232:235], v143 offset:55296
	ds_read_b128 v[236:239], v143 offset:56320
	global_load_lds_dwordx4 v[138:139], off
	s_add_i32 m0, s54, 0x2000
	s_add_u32 s42, s42, 0x40080
	v_lshl_add_u64 v[138:139], v[240:241], 0, s[48:49]
	s_addc_u32 s43, s43, 0
	s_add_i32 s54, s60, s36
	global_load_lds_dwordx4 v[138:139], off
	v_lshl_add_u64 v[138:139], s[42:43], 0, v[144:145]
	s_mov_b32 m0, s54
	s_nop 0
	global_load_lds_dwordx4 v[138:139], off
	v_lshl_add_u64 v[138:139], s[42:43], 0, v[128:129]
	s_add_i32 m0, s54, 0x2000
	s_nop 0
	global_load_lds_dwordx4 v[138:139], off
	v_lshl_add_u64 v[138:139], v[242:243], 0, s[48:49]
	s_mov_b32 m0, s45
	s_nop 0
	global_load_lds_dwordx4 v[138:139], off
	v_lshl_add_u64 v[138:139], v[244:245], 0, s[48:49]
	s_mov_b32 m0, s46
	s_nop 0
	global_load_lds_dwordx4 v[138:139], off
	s_waitcnt vmcnt(8)
	s_waitcnt lgkmcnt(0)
	s_barrier
	s_waitcnt lgkmcnt(0)
	v_mfma_f32_16x16x32_bf16 v[60:63], v[154:157], v[208:211], v[60:63]
	v_mfma_f32_16x16x32_bf16 v[52:55], v[162:165], v[208:211], v[52:55]
	v_mfma_f32_16x16x32_bf16 v[44:47], v[154:157], v[216:219], v[44:47]
	v_mfma_f32_16x16x32_bf16 v[36:39], v[162:165], v[216:219], v[36:39]
	v_mfma_f32_16x16x32_bf16 v[28:31], v[154:157], v[224:227], v[28:31]
	v_mfma_f32_16x16x32_bf16 v[20:23], v[162:165], v[224:227], v[20:23]
	v_mfma_f32_16x16x32_bf16 v[12:15], v[154:157], v[232:235], v[12:15]
	v_mfma_f32_16x16x32_bf16 v[4:7], v[162:165], v[232:235], v[4:7]
	v_mfma_f32_16x16x32_bf16 v[60:63], v[158:161], v[212:215], v[60:63]
	v_mfma_f32_16x16x32_bf16 v[52:55], v[166:169], v[212:215], v[52:55]
	v_mfma_f32_16x16x32_bf16 v[44:47], v[158:161], v[220:223], v[44:47]
	v_mfma_f32_16x16x32_bf16 v[36:39], v[166:169], v[220:223], v[36:39]
	v_mfma_f32_16x16x32_bf16 v[28:31], v[158:161], v[228:231], v[28:31]
	v_mfma_f32_16x16x32_bf16 v[20:23], v[166:169], v[228:231], v[20:23]
	v_mfma_f32_16x16x32_bf16 v[12:15], v[158:161], v[236:239], v[12:15]
	v_mfma_f32_16x16x32_bf16 v[4:7], v[166:169], v[236:239], v[4:7]
	v_mfma_f32_16x16x32_bf16 v[56:59], v[170:173], v[208:211], v[56:59]
	v_mfma_f32_16x16x32_bf16 v[48:51], v[178:181], v[208:211], v[48:51]
	v_mfma_f32_16x16x32_bf16 v[40:43], v[170:173], v[216:219], v[40:43]
	v_mfma_f32_16x16x32_bf16 v[32:35], v[178:181], v[216:219], v[32:35]
	v_mfma_f32_16x16x32_bf16 v[24:27], v[170:173], v[224:227], v[24:27]
	v_mfma_f32_16x16x32_bf16 v[16:19], v[178:181], v[224:227], v[16:19]
	v_mfma_f32_16x16x32_bf16 v[8:11], v[170:173], v[232:235], v[8:11]
	v_mfma_f32_16x16x32_bf16 v[0:3], v[178:181], v[232:235], v[0:3]
	v_mfma_f32_16x16x32_bf16 v[56:59], v[174:177], v[212:215], v[56:59]
	v_mfma_f32_16x16x32_bf16 v[48:51], v[204:207], v[212:215], v[48:51]
	v_mfma_f32_16x16x32_bf16 v[40:43], v[174:177], v[220:223], v[40:43]
	v_mfma_f32_16x16x32_bf16 v[32:35], v[204:207], v[220:223], v[32:35]
	v_mfma_f32_16x16x32_bf16 v[24:27], v[174:177], v[228:231], v[24:27]
	v_mfma_f32_16x16x32_bf16 v[16:19], v[204:207], v[228:231], v[16:19]
	v_mfma_f32_16x16x32_bf16 v[8:11], v[174:177], v[236:239], v[8:11]
	v_mfma_f32_16x16x32_bf16 v[0:3], v[204:207], v[236:239], v[0:3]
	s_barrier
	s_add_i32 s58, s58, 2
	s_add_u32 s56, s56, 0x100
	s_addc_u32 s57, s57, 0
	s_add_u32 s51, s51, 0x100
	s_addc_u32 s53, s53, 0
	s_cmp_gt_u32 s58, 13
	s_cbranch_scc0 .LBB0_345
	s_and_b64 vcc, exec, s[6:7]
	s_cbranch_vccz .LBB0_348
	s_barrier

.LBB0_459:
	s_add_u32 s20, s18, 0x100
	s_addc_u32 s21, s19, 0
	s_add_i32 s58, 0, 0x10000
	s_cmp_eq_u32 s57, 18
	s_cselect_b32 s25, s5, s21
	s_cselect_b32 s24, s4, s20
	v_add_u32_e32 v140, s58, v143
	s_cselect_b32 s23, s15, s56
	s_cselect_b32 s22, s14, s17
	s_add_i32 s59, 0, 0x14000
	ds_read_b128 v[156:159], v140
	ds_read_b128 v[160:163], v140 offset:1024
	ds_read_b128 v[164:167], v140 offset:2048
	ds_read_b128 v[168:171], v140 offset:3072
	v_add_u32_e32 v140, s59, v143
	ds_read_b128 v[172:175], v140
	ds_read_b128 v[176:179], v140 offset:1024
	ds_read_b128 v[204:207], v140 offset:2048
	ds_read_b128 v[208:211], v140 offset:3072
	v_lshl_add_u64 v[140:141], s[18:19], 0, v[136:137]
	s_add_i32 m0, s37, 0xc000
	ds_read_b128 v[212:215], v154
	ds_read_b128 v[216:219], v154 offset:1024
	ds_read_b128 v[220:223], v154 offset:2048
	ds_read_b128 v[224:227], v154 offset:3072
	ds_read_b128 v[228:231], v154 offset:4096
	ds_read_b128 v[232:235], v154 offset:5120
	ds_read_b128 v[236:239], v154 offset:6144
	ds_read_b128 v[240:243], v154 offset:7168
	global_load_lds_dwordx4 v[140:141], off
	v_lshl_add_u64 v[140:141], s[18:19], 0, v[138:139]
	s_add_i32 m0, s37, 0xe000
	s_nop 0
	global_load_lds_dwordx4 v[140:141], off
	s_waitcnt vmcnt(8)
	s_waitcnt lgkmcnt(0)
	s_barrier
	s_waitcnt lgkmcnt(0)
	v_mfma_f32_16x16x32_bf16 v[124:127], v[156:159], v[212:215], v[124:127]
	v_mfma_f32_16x16x32_bf16 v[120:123], v[164:167], v[212:215], v[120:123]
	v_mfma_f32_16x16x32_bf16 v[116:119], v[156:159], v[220:223], v[116:119]
	v_mfma_f32_16x16x32_bf16 v[108:111], v[164:167], v[220:223], v[108:111]
	v_mfma_f32_16x16x32_bf16 v[100:103], v[156:159], v[228:231], v[100:103]
	v_mfma_f32_16x16x32_bf16 v[92:95], v[164:167], v[228:231], v[92:95]
	v_mfma_f32_16x16x32_bf16 v[84:87], v[156:159], v[236:239], v[84:87]
	v_mfma_f32_16x16x32_bf16 v[76:79], v[164:167], v[236:239], v[76:79]
	v_mfma_f32_16x16x32_bf16 v[124:127], v[160:163], v[216:219], v[124:127]
	v_mfma_f32_16x16x32_bf16 v[120:123], v[168:171], v[216:219], v[120:123]
	v_mfma_f32_16x16x32_bf16 v[116:119], v[160:163], v[224:227], v[116:119]
	v_mfma_f32_16x16x32_bf16 v[108:111], v[168:171], v[224:227], v[108:111]
	v_mfma_f32_16x16x32_bf16 v[100:103], v[160:163], v[232:235], v[100:103]
	v_mfma_f32_16x16x32_bf16 v[92:95], v[168:171], v[232:235], v[92:95]
	v_mfma_f32_16x16x32_bf16 v[84:87], v[160:163], v[240:243], v[84:87]
	v_mfma_f32_16x16x32_bf16 v[76:79], v[168:171], v[240:243], v[76:79]
	v_mfma_f32_16x16x32_bf16 v[112:115], v[172:175], v[212:215], v[112:115]
	v_mfma_f32_16x16x32_bf16 v[104:107], v[204:207], v[212:215], v[104:107]
	v_mfma_f32_16x16x32_bf16 v[96:99], v[172:175], v[220:223], v[96:99]
	v_mfma_f32_16x16x32_bf16 v[88:91], v[204:207], v[220:223], v[88:91]
	v_mfma_f32_16x16x32_bf16 v[80:83], v[172:175], v[228:231], v[80:83]
	v_mfma_f32_16x16x32_bf16 v[72:75], v[204:207], v[228:231], v[72:75]
	v_mfma_f32_16x16x32_bf16 v[68:71], v[172:175], v[236:239], v[68:71]
	v_mfma_f32_16x16x32_bf16 v[64:67], v[204:207], v[236:239], v[64:67]
	v_mfma_f32_16x16x32_bf16 v[112:115], v[176:179], v[216:219], v[112:115]
	v_mfma_f32_16x16x32_bf16 v[104:107], v[208:211], v[216:219], v[104:107]
	v_mfma_f32_16x16x32_bf16 v[96:99], v[176:179], v[224:227], v[96:99]
	v_mfma_f32_16x16x32_bf16 v[88:91], v[208:211], v[224:227], v[88:91]
	v_mfma_f32_16x16x32_bf16 v[80:83], v[176:179], v[232:235], v[80:83]
	v_mfma_f32_16x16x32_bf16 v[72:75], v[208:211], v[232:235], v[72:75]
	v_mfma_f32_16x16x32_bf16 v[68:71], v[176:179], v[240:243], v[68:71]
	v_mfma_f32_16x16x32_bf16 v[64:67], v[208:211], v[240:243], v[64:67]
	s_barrier
	s_add_i32 s18, s58, s36
	v_lshl_add_u64 v[140:141], s[22:23], 0, v[130:131]
	s_mov_b32 m0, s18
	ds_read_b128 v[212:215], v154 offset:16384
	ds_read_b128 v[216:219], v154 offset:17408
	ds_read_b128 v[220:223], v154 offset:18432
	ds_read_b128 v[224:227], v154 offset:19456
	ds_read_b128 v[228:231], v154 offset:20480
	ds_read_b128 v[232:235], v154 offset:21504
	ds_read_b128 v[236:239], v154 offset:22528
	ds_read_b128 v[240:243], v154 offset:23552
	global_load_lds_dwordx4 v[140:141], off
	s_add_i32 m0, s18, 0x2000
	s_add_u32 s18, s22, 0xb0000
	v_lshl_add_u64 v[180:181], s[22:23], 0, v[134:135]
	s_addc_u32 s19, s23, 0
	s_add_i32 s58, s59, s36
	global_load_lds_dwordx4 v[180:181], off
	v_lshl_add_u64 v[244:245], s[18:19], 0, v[130:131]
	s_mov_b32 m0, s58
	v_lshl_add_u64 v[246:247], s[24:25], 0, v[132:133]
	global_load_lds_dwordx4 v[244:245], off
	v_lshl_add_u64 v[244:245], s[18:19], 0, v[134:135]
	s_add_i32 m0, s58, 0x2000
	s_nop 0
	global_load_lds_dwordx4 v[244:245], off
	v_lshl_add_u64 v[244:245], s[24:25], 0, v[128:129]
	s_mov_b32 m0, s37
	s_nop 0
	global_load_lds_dwordx4 v[244:245], off
	s_mov_b32 m0, s40
	s_nop 0
	global_load_lds_dwordx4 v[246:247], off
	s_waitcnt vmcnt(8)
	s_waitcnt lgkmcnt(0)
	s_barrier
	s_waitcnt lgkmcnt(0)
	v_mfma_f32_16x16x32_bf16 v[60:63], v[156:159], v[212:215], v[60:63]
	v_mfma_f32_16x16x32_bf16 v[56:59], v[164:167], v[212:215], v[56:59]
	v_mfma_f32_16x16x32_bf16 v[52:55], v[156:159], v[220:223], v[52:55]
	v_mfma_f32_16x16x32_bf16 v[44:47], v[164:167], v[220:223], v[44:47]
	v_mfma_f32_16x16x32_bf16 v[36:39], v[156:159], v[228:231], v[36:39]
	v_mfma_f32_16x16x32_bf16 v[28:31], v[164:167], v[228:231], v[28:31]
	v_mfma_f32_16x16x32_bf16 v[20:23], v[156:159], v[236:239], v[20:23]
	v_mfma_f32_16x16x32_bf16 v[12:15], v[164:167], v[236:239], v[12:15]
	v_mfma_f32_16x16x32_bf16 v[60:63], v[160:163], v[216:219], v[60:63]
	v_mfma_f32_16x16x32_bf16 v[56:59], v[168:171], v[216:219], v[56:59]
	v_mfma_f32_16x16x32_bf16 v[52:55], v[160:163], v[224:227], v[52:55]
	v_mfma_f32_16x16x32_bf16 v[44:47], v[168:171], v[224:227], v[44:47]
	v_mfma_f32_16x16x32_bf16 v[36:39], v[160:163], v[232:235], v[36:39]
	v_mfma_f32_16x16x32_bf16 v[28:31], v[168:171], v[232:235], v[28:31]
	v_mfma_f32_16x16x32_bf16 v[20:23], v[160:163], v[240:243], v[20:23]
	v_mfma_f32_16x16x32_bf16 v[12:15], v[168:171], v[240:243], v[12:15]
	v_mfma_f32_16x16x32_bf16 v[48:51], v[172:175], v[212:215], v[48:51]
	v_mfma_f32_16x16x32_bf16 v[40:43], v[204:207], v[212:215], v[40:43]
	v_mfma_f32_16x16x32_bf16 v[32:35], v[172:175], v[220:223], v[32:35]
	v_mfma_f32_16x16x32_bf16 v[24:27], v[204:207], v[220:223], v[24:27]
	v_mfma_f32_16x16x32_bf16 v[16:19], v[172:175], v[228:231], v[16:19]
	v_mfma_f32_16x16x32_bf16 v[8:11], v[204:207], v[228:231], v[8:11]
	v_mfma_f32_16x16x32_bf16 v[4:7], v[172:175], v[236:239], v[4:7]
	v_mfma_f32_16x16x32_bf16 v[0:3], v[204:207], v[236:239], v[0:3]
	v_mfma_f32_16x16x32_bf16 v[48:51], v[176:179], v[216:219], v[48:51]
	v_mfma_f32_16x16x32_bf16 v[40:43], v[208:211], v[216:219], v[40:43]
	v_mfma_f32_16x16x32_bf16 v[32:35], v[176:179], v[224:227], v[32:35]
	v_mfma_f32_16x16x32_bf16 v[24:27], v[208:211], v[224:227], v[24:27]
	v_mfma_f32_16x16x32_bf16 v[16:19], v[176:179], v[232:235], v[16:19]
	v_mfma_f32_16x16x32_bf16 v[8:11], v[208:211], v[232:235], v[8:11]
	v_mfma_f32_16x16x32_bf16 v[4:7], v[176:179], v[240:243], v[4:7]
	v_mfma_f32_16x16x32_bf16 v[0:3], v[208:211], v[240:243], v[0:3]
	s_barrier
	s_add_i32 s58, 0, 0x18000
	v_add_u32_e32 v155, s58, v143
	s_add_i32 s59, 0, 0x1c000
	ds_read_b128 v[156:159], v155
	ds_read_b128 v[160:163], v155 offset:1024
	ds_read_b128 v[164:167], v155 offset:2048
	ds_read_b128 v[168:171], v155 offset:3072
	v_add_u32_e32 v155, s59, v143
	ds_read_b128 v[172:175], v155
	ds_read_b128 v[176:179], v155 offset:1024
	ds_read_b128 v[204:207], v155 offset:2048
	ds_read_b128 v[208:211], v155 offset:3072
	s_add_u32 s18, s24, 0xb0000
	s_addc_u32 s19, s25, 0
	s_mov_b32 m0, s41
	v_lshl_add_u64 v[248:249], s[18:19], 0, v[128:129]
	ds_read_b128 v[212:215], v154 offset:32768
	ds_read_b128 v[216:219], v154 offset:33792
	ds_read_b128 v[220:223], v154 offset:34816
	ds_read_b128 v[224:227], v154 offset:35840
	ds_read_b128 v[228:231], v154 offset:36864
	ds_read_b128 v[232:235], v154 offset:37888
	ds_read_b128 v[236:239], v154 offset:38912
	ds_read_b128 v[240:243], v154 offset:39936
	global_load_lds_dwordx4 v[248:249], off
	v_lshl_add_u64 v[248:249], s[18:19], 0, v[132:133]
	s_mov_b32 m0, s42
	s_nop 0
	global_load_lds_dwordx4 v[248:249], off
	s_waitcnt vmcnt(8)
	s_waitcnt lgkmcnt(0)
	s_barrier
	s_waitcnt lgkmcnt(0)
	v_mfma_f32_16x16x32_bf16 v[124:127], v[156:159], v[212:215], v[124:127]
	v_mfma_f32_16x16x32_bf16 v[120:123], v[164:167], v[212:215], v[120:123]
	v_mfma_f32_16x16x32_bf16 v[116:119], v[156:159], v[220:223], v[116:119]
	v_mfma_f32_16x16x32_bf16 v[108:111], v[164:167], v[220:223], v[108:111]
	v_mfma_f32_16x16x32_bf16 v[100:103], v[156:159], v[228:231], v[100:103]
	v_mfma_f32_16x16x32_bf16 v[92:95], v[164:167], v[228:231], v[92:95]
	v_mfma_f32_16x16x32_bf16 v[84:87], v[156:159], v[236:239], v[84:87]
	v_mfma_f32_16x16x32_bf16 v[76:79], v[164:167], v[236:239], v[76:79]
	v_mfma_f32_16x16x32_bf16 v[124:127], v[160:163], v[216:219], v[124:127]
	v_mfma_f32_16x16x32_bf16 v[120:123], v[168:171], v[216:219], v[120:123]
	v_mfma_f32_16x16x32_bf16 v[116:119], v[160:163], v[224:227], v[116:119]
	v_mfma_f32_16x16x32_bf16 v[108:111], v[168:171], v[224:227], v[108:111]
	v_mfma_f32_16x16x32_bf16 v[100:103], v[160:163], v[232:235], v[100:103]
	v_mfma_f32_16x16x32_bf16 v[92:95], v[168:171], v[232:235], v[92:95]
	v_mfma_f32_16x16x32_bf16 v[84:87], v[160:163], v[240:243], v[84:87]
	v_mfma_f32_16x16x32_bf16 v[76:79], v[168:171], v[240:243], v[76:79]
	v_mfma_f32_16x16x32_bf16 v[112:115], v[172:175], v[212:215], v[112:115]
	v_mfma_f32_16x16x32_bf16 v[104:107], v[204:207], v[212:215], v[104:107]
	v_mfma_f32_16x16x32_bf16 v[96:99], v[172:175], v[220:223], v[96:99]
	v_mfma_f32_16x16x32_bf16 v[88:91], v[204:207], v[220:223], v[88:91]
	v_mfma_f32_16x16x32_bf16 v[80:83], v[172:175], v[228:231], v[80:83]
	v_mfma_f32_16x16x32_bf16 v[72:75], v[204:207], v[228:231], v[72:75]
	v_mfma_f32_16x16x32_bf16 v[68:71], v[172:175], v[236:239], v[68:71]
	v_mfma_f32_16x16x32_bf16 v[64:67], v[204:207], v[236:239], v[64:67]
	v_mfma_f32_16x16x32_bf16 v[112:115], v[176:179], v[216:219], v[112:115]
	v_mfma_f32_16x16x32_bf16 v[104:107], v[208:211], v[216:219], v[104:107]
	v_mfma_f32_16x16x32_bf16 v[96:99], v[176:179], v[224:227], v[96:99]
	v_mfma_f32_16x16x32_bf16 v[88:91], v[208:211], v[224:227], v[88:91]
	v_mfma_f32_16x16x32_bf16 v[80:83], v[176:179], v[232:235], v[80:83]
	v_mfma_f32_16x16x32_bf16 v[72:75], v[208:211], v[232:235], v[72:75]
	v_mfma_f32_16x16x32_bf16 v[68:71], v[176:179], v[240:243], v[68:71]
	v_mfma_f32_16x16x32_bf16 v[64:67], v[208:211], v[240:243], v[64:67]
	s_barrier
	s_add_i32 s18, s58, s36
	v_lshl_add_u64 v[140:141], v[140:141], 0, s[48:49]
	s_mov_b32 m0, s18
	ds_read_b128 v[212:215], v154 offset:49152
	ds_read_b128 v[216:219], v154 offset:50176
	ds_read_b128 v[220:223], v154 offset:51200
	ds_read_b128 v[224:227], v154 offset:52224
	ds_read_b128 v[228:231], v154 offset:53248
	ds_read_b128 v[232:235], v154 offset:54272
	ds_read_b128 v[236:239], v154 offset:55296
	ds_read_b128 v[240:243], v154 offset:56320
	global_load_lds_dwordx4 v[140:141], off
	s_add_i32 m0, s18, 0x2000
	s_add_u32 s18, s22, 0xb0080
	v_lshl_add_u64 v[140:141], v[180:181], 0, s[48:49]
	s_addc_u32 s19, s23, 0
	s_add_i32 s22, s59, s36
	global_load_lds_dwordx4 v[140:141], off
	v_lshl_add_u64 v[140:141], s[18:19], 0, v[130:131]
	s_mov_b32 m0, s22
	s_nop 0
	global_load_lds_dwordx4 v[140:141], off
	v_lshl_add_u64 v[140:141], s[18:19], 0, v[134:135]
	s_add_i32 m0, s22, 0x2000
	s_nop 0
	global_load_lds_dwordx4 v[140:141], off
	v_lshl_add_u64 v[140:141], v[244:245], 0, s[48:49]
	s_mov_b32 m0, s43
	s_nop 0
	global_load_lds_dwordx4 v[140:141], off
	v_lshl_add_u64 v[140:141], v[246:247], 0, s[48:49]
	s_mov_b32 m0, s44
	s_nop 0
	global_load_lds_dwordx4 v[140:141], off
	s_waitcnt vmcnt(8)
	s_waitcnt lgkmcnt(0)
	s_barrier
	s_waitcnt lgkmcnt(0)
	v_mfma_f32_16x16x32_bf16 v[60:63], v[156:159], v[212:215], v[60:63]
	v_mfma_f32_16x16x32_bf16 v[56:59], v[164:167], v[212:215], v[56:59]
	v_mfma_f32_16x16x32_bf16 v[52:55], v[156:159], v[220:223], v[52:55]
	v_mfma_f32_16x16x32_bf16 v[44:47], v[164:167], v[220:223], v[44:47]
	v_mfma_f32_16x16x32_bf16 v[36:39], v[156:159], v[228:231], v[36:39]
	v_mfma_f32_16x16x32_bf16 v[28:31], v[164:167], v[228:231], v[28:31]
	v_mfma_f32_16x16x32_bf16 v[20:23], v[156:159], v[236:239], v[20:23]
	v_mfma_f32_16x16x32_bf16 v[12:15], v[164:167], v[236:239], v[12:15]
	v_mfma_f32_16x16x32_bf16 v[60:63], v[160:163], v[216:219], v[60:63]
	v_mfma_f32_16x16x32_bf16 v[56:59], v[168:171], v[216:219], v[56:59]
	v_mfma_f32_16x16x32_bf16 v[52:55], v[160:163], v[224:227], v[52:55]
	v_mfma_f32_16x16x32_bf16 v[44:47], v[168:171], v[224:227], v[44:47]
	v_mfma_f32_16x16x32_bf16 v[36:39], v[160:163], v[232:235], v[36:39]
	v_mfma_f32_16x16x32_bf16 v[28:31], v[168:171], v[232:235], v[28:31]
	v_mfma_f32_16x16x32_bf16 v[20:23], v[160:163], v[240:243], v[20:23]
	v_mfma_f32_16x16x32_bf16 v[12:15], v[168:171], v[240:243], v[12:15]
	v_mfma_f32_16x16x32_bf16 v[48:51], v[172:175], v[212:215], v[48:51]
	v_mfma_f32_16x16x32_bf16 v[40:43], v[204:207], v[212:215], v[40:43]
	v_mfma_f32_16x16x32_bf16 v[32:35], v[172:175], v[220:223], v[32:35]
	v_mfma_f32_16x16x32_bf16 v[24:27], v[204:207], v[220:223], v[24:27]
	v_mfma_f32_16x16x32_bf16 v[16:19], v[172:175], v[228:231], v[16:19]
	v_mfma_f32_16x16x32_bf16 v[8:11], v[204:207], v[228:231], v[8:11]
	v_mfma_f32_16x16x32_bf16 v[4:7], v[172:175], v[236:239], v[4:7]
	v_mfma_f32_16x16x32_bf16 v[0:3], v[204:207], v[236:239], v[0:3]
	v_mfma_f32_16x16x32_bf16 v[48:51], v[176:179], v[216:219], v[48:51]
	v_mfma_f32_16x16x32_bf16 v[40:43], v[208:211], v[216:219], v[40:43]
	v_mfma_f32_16x16x32_bf16 v[32:35], v[176:179], v[224:227], v[32:35]
	v_mfma_f32_16x16x32_bf16 v[24:27], v[208:211], v[224:227], v[24:27]
	v_mfma_f32_16x16x32_bf16 v[16:19], v[176:179], v[232:235], v[16:19]
	v_mfma_f32_16x16x32_bf16 v[8:11], v[208:211], v[232:235], v[8:11]
	v_mfma_f32_16x16x32_bf16 v[4:7], v[176:179], v[240:243], v[4:7]
	v_mfma_f32_16x16x32_bf16 v[0:3], v[208:211], v[240:243], v[0:3]
	s_barrier
	s_add_i32 s57, s57, 2
	s_add_u32 s17, s17, 0x100
	s_addc_u32 s56, s56, 0
	s_cmp_gt_u32 s57, 19
	s_mov_b64 s[18:19], s[20:21]
	s_cbranch_scc0 .LBB0_459
	s_and_b64 vcc, exec, s[12:13]
	s_cbranch_vccz .LBB0_462
	s_barrier

.LBB0_594:
	s_add_u32 s37, s4, 0xfffc0080
	s_addc_u32 s38, s5, -1
	s_add_i32 s40, 0, 0x10000
	s_cmp_eq_u32 s36, 12
	s_cselect_b32 s55, s7, s38
	s_cselect_b32 s54, s9, s37
	v_add_u32_e32 v144, s40, v141
	s_cselect_b32 s43, s26, s31
	s_cselect_b32 s42, s27, s30
	s_add_i32 s37, 0, 0x14000
	ds_read_b128 v[128:131], v144
	ds_read_b128 v[166:169], v144 offset:1024
	ds_read_b128 v[170:173], v144 offset:2048
	ds_read_b128 v[174:177], v144 offset:3072
	v_add_u32_e32 v144, s37, v141
	ds_read_b128 v[178:181], v144
	ds_read_b128 v[204:207], v144 offset:1024
	ds_read_b128 v[208:211], v144 offset:2048
	ds_read_b128 v[212:215], v144 offset:3072
	v_lshl_add_u64 v[248:249], s[4:5], 0, v[162:163]
	s_add_i32 m0, s87, 0xc000
	ds_read_b128 v[216:219], v155
	ds_read_b128 v[220:223], v155 offset:1024
	ds_read_b128 v[224:227], v155 offset:2048
	ds_read_b128 v[228:231], v155 offset:3072
	ds_read_b128 v[232:235], v155 offset:4096
	ds_read_b128 v[236:239], v155 offset:5120
	ds_read_b128 v[240:243], v155 offset:6144
	ds_read_b128 v[244:247], v155 offset:7168
	global_load_lds_dwordx4 v[248:249], off
	v_lshl_add_u64 v[248:249], s[4:5], 0, v[164:165]
	s_add_i32 m0, s87, 0xe000
	s_nop 0
	global_load_lds_dwordx4 v[248:249], off
	s_waitcnt vmcnt(8)
	s_waitcnt lgkmcnt(0)
	s_barrier
	s_waitcnt lgkmcnt(0)
	v_mfma_f32_16x16x32_bf16 v[124:127], v[128:131], v[216:219], v[124:127]
	v_mfma_f32_16x16x32_bf16 v[120:123], v[170:173], v[216:219], v[120:123]
	v_mfma_f32_16x16x32_bf16 v[108:111], v[128:131], v[224:227], v[108:111]
	v_mfma_f32_16x16x32_bf16 v[104:107], v[170:173], v[224:227], v[104:107]
	v_mfma_f32_16x16x32_bf16 v[92:95], v[128:131], v[232:235], v[92:95]
	v_mfma_f32_16x16x32_bf16 v[88:91], v[170:173], v[232:235], v[88:91]
	v_mfma_f32_16x16x32_bf16 v[76:79], v[128:131], v[240:243], v[76:79]
	v_mfma_f32_16x16x32_bf16 v[72:75], v[170:173], v[240:243], v[72:75]
	v_mfma_f32_16x16x32_bf16 v[124:127], v[166:169], v[220:223], v[124:127]
	v_mfma_f32_16x16x32_bf16 v[120:123], v[174:177], v[220:223], v[120:123]
	v_mfma_f32_16x16x32_bf16 v[108:111], v[166:169], v[228:231], v[108:111]
	v_mfma_f32_16x16x32_bf16 v[104:107], v[174:177], v[228:231], v[104:107]
	v_mfma_f32_16x16x32_bf16 v[92:95], v[166:169], v[236:239], v[92:95]
	v_mfma_f32_16x16x32_bf16 v[88:91], v[174:177], v[236:239], v[88:91]
	v_mfma_f32_16x16x32_bf16 v[76:79], v[166:169], v[244:247], v[76:79]
	v_mfma_f32_16x16x32_bf16 v[72:75], v[174:177], v[244:247], v[72:75]
	v_mfma_f32_16x16x32_bf16 v[116:119], v[178:181], v[216:219], v[116:119]
	v_mfma_f32_16x16x32_bf16 v[112:115], v[208:211], v[216:219], v[112:115]
	v_mfma_f32_16x16x32_bf16 v[100:103], v[178:181], v[224:227], v[100:103]
	v_mfma_f32_16x16x32_bf16 v[96:99], v[208:211], v[224:227], v[96:99]
	v_mfma_f32_16x16x32_bf16 v[84:87], v[178:181], v[232:235], v[84:87]
	v_mfma_f32_16x16x32_bf16 v[80:83], v[208:211], v[232:235], v[80:83]
	v_mfma_f32_16x16x32_bf16 v[68:71], v[178:181], v[240:243], v[68:71]
	v_mfma_f32_16x16x32_bf16 v[64:67], v[208:211], v[240:243], v[64:67]
	v_mfma_f32_16x16x32_bf16 v[116:119], v[204:207], v[220:223], v[116:119]
	v_mfma_f32_16x16x32_bf16 v[112:115], v[212:215], v[220:223], v[112:115]
	v_mfma_f32_16x16x32_bf16 v[100:103], v[204:207], v[228:231], v[100:103]
	v_mfma_f32_16x16x32_bf16 v[96:99], v[212:215], v[228:231], v[96:99]
	v_mfma_f32_16x16x32_bf16 v[84:87], v[204:207], v[236:239], v[84:87]
	v_mfma_f32_16x16x32_bf16 v[80:83], v[212:215], v[236:239], v[80:83]
	v_mfma_f32_16x16x32_bf16 v[68:71], v[204:207], v[244:247], v[68:71]
	v_mfma_f32_16x16x32_bf16 v[64:67], v[212:215], v[244:247], v[64:67]
	s_barrier
	s_add_i32 s38, s40, s86
	v_lshl_add_u64 v[248:249], s[42:43], 0, v[134:135]
	s_mov_b32 m0, s38
	ds_read_b128 v[216:219], v155 offset:16384
	ds_read_b128 v[220:223], v155 offset:17408
	ds_read_b128 v[224:227], v155 offset:18432
	ds_read_b128 v[228:231], v155 offset:19456
	ds_read_b128 v[232:235], v155 offset:20480
	ds_read_b128 v[236:239], v155 offset:21504
	ds_read_b128 v[240:243], v155 offset:22528
	ds_read_b128 v[244:247], v155 offset:23552
	global_load_lds_dwordx4 v[248:249], off
	s_add_i32 m0, s38, 0x2000
	s_add_u32 s44, s42, 0x40000
	v_lshl_add_u64 v[250:251], s[42:43], 0, v[138:139]
	s_addc_u32 s45, s43, 0
	s_add_i32 s37, s37, s86
	global_load_lds_dwordx4 v[250:251], off
	v_lshl_add_u64 v[252:253], s[44:45], 0, v[134:135]
	s_mov_b32 m0, s37
	v_lshl_add_u64 v[190:191], s[54:55], 0, v[136:137]
	global_load_lds_dwordx4 v[252:253], off
	v_lshl_add_u64 v[252:253], s[44:45], 0, v[138:139]
	s_add_i32 m0, s37, 0x2000
	s_nop 0
	global_load_lds_dwordx4 v[252:253], off
	v_lshl_add_u64 v[252:253], s[54:55], 0, v[132:133]
	s_mov_b32 m0, s87
	s_nop 0
	global_load_lds_dwordx4 v[252:253], off
	s_mov_b32 m0, s76
	s_nop 0
	global_load_lds_dwordx4 v[190:191], off
	s_waitcnt vmcnt(8)
	s_waitcnt lgkmcnt(0)
	s_barrier
	s_waitcnt lgkmcnt(0)
	v_mfma_f32_16x16x32_bf16 v[60:63], v[128:131], v[216:219], v[60:63]
	v_mfma_f32_16x16x32_bf16 v[56:59], v[170:173], v[216:219], v[56:59]
	v_mfma_f32_16x16x32_bf16 v[44:47], v[128:131], v[224:227], v[44:47]
	v_mfma_f32_16x16x32_bf16 v[40:43], v[170:173], v[224:227], v[40:43]
	v_mfma_f32_16x16x32_bf16 v[28:31], v[128:131], v[232:235], v[28:31]
	v_mfma_f32_16x16x32_bf16 v[24:27], v[170:173], v[232:235], v[24:27]
	v_mfma_f32_16x16x32_bf16 v[12:15], v[128:131], v[240:243], v[12:15]
	v_mfma_f32_16x16x32_bf16 v[8:11], v[170:173], v[240:243], v[8:11]
	v_mfma_f32_16x16x32_bf16 v[60:63], v[166:169], v[220:223], v[60:63]
	v_mfma_f32_16x16x32_bf16 v[56:59], v[174:177], v[220:223], v[56:59]
	v_mfma_f32_16x16x32_bf16 v[44:47], v[166:169], v[228:231], v[44:47]
	v_mfma_f32_16x16x32_bf16 v[40:43], v[174:177], v[228:231], v[40:43]
	v_mfma_f32_16x16x32_bf16 v[28:31], v[166:169], v[236:239], v[28:31]
	v_mfma_f32_16x16x32_bf16 v[24:27], v[174:177], v[236:239], v[24:27]
	v_mfma_f32_16x16x32_bf16 v[12:15], v[166:169], v[244:247], v[12:15]
	v_mfma_f32_16x16x32_bf16 v[8:11], v[174:177], v[244:247], v[8:11]
	v_mfma_f32_16x16x32_bf16 v[52:55], v[178:181], v[216:219], v[52:55]
	v_mfma_f32_16x16x32_bf16 v[48:51], v[208:211], v[216:219], v[48:51]
	v_mfma_f32_16x16x32_bf16 v[36:39], v[178:181], v[224:227], v[36:39]
	v_mfma_f32_16x16x32_bf16 v[32:35], v[208:211], v[224:227], v[32:35]
	v_mfma_f32_16x16x32_bf16 v[20:23], v[178:181], v[232:235], v[20:23]
	v_mfma_f32_16x16x32_bf16 v[16:19], v[208:211], v[232:235], v[16:19]
	v_mfma_f32_16x16x32_bf16 v[4:7], v[178:181], v[240:243], v[4:7]
	v_mfma_f32_16x16x32_bf16 v[0:3], v[208:211], v[240:243], v[0:3]
	v_mfma_f32_16x16x32_bf16 v[52:55], v[204:207], v[220:223], v[52:55]
	v_mfma_f32_16x16x32_bf16 v[48:51], v[212:215], v[220:223], v[48:51]
	v_mfma_f32_16x16x32_bf16 v[36:39], v[204:207], v[228:231], v[36:39]
	v_mfma_f32_16x16x32_bf16 v[32:35], v[212:215], v[228:231], v[32:35]
	v_mfma_f32_16x16x32_bf16 v[20:23], v[204:207], v[236:239], v[20:23]
	v_mfma_f32_16x16x32_bf16 v[16:19], v[212:215], v[236:239], v[16:19]
	v_mfma_f32_16x16x32_bf16 v[4:7], v[204:207], v[244:247], v[4:7]
	v_mfma_f32_16x16x32_bf16 v[0:3], v[212:215], v[244:247], v[0:3]
	s_barrier
	s_add_i32 s37, 0, 0x18000
	v_add_u32_e32 v144, s37, v141
	s_add_i32 s38, 0, 0x1c000
	ds_read_b128 v[128:131], v144
	ds_read_b128 v[166:169], v144 offset:1024
	ds_read_b128 v[170:173], v144 offset:2048
	ds_read_b128 v[174:177], v144 offset:3072
	v_add_u32_e32 v144, s38, v141
	ds_read_b128 v[178:181], v144
	ds_read_b128 v[204:207], v144 offset:1024
	ds_read_b128 v[208:211], v144 offset:2048
	ds_read_b128 v[212:215], v144 offset:3072
	s_add_u32 s44, s54, 0x40000
	s_addc_u32 s45, s55, 0
	s_mov_b32 m0, s77
	v_lshl_add_u64 v[192:193], s[44:45], 0, v[132:133]
	ds_read_b128 v[216:219], v155 offset:32768
	ds_read_b128 v[220:223], v155 offset:33792
	ds_read_b128 v[224:227], v155 offset:34816
	ds_read_b128 v[228:231], v155 offset:35840
	ds_read_b128 v[232:235], v155 offset:36864
	ds_read_b128 v[236:239], v155 offset:37888
	ds_read_b128 v[240:243], v155 offset:38912
	ds_read_b128 v[244:247], v155 offset:39936
	global_load_lds_dwordx4 v[192:193], off
	v_lshl_add_u64 v[192:193], s[44:45], 0, v[136:137]
	s_mov_b32 m0, s74
	s_nop 0
	global_load_lds_dwordx4 v[192:193], off
	s_waitcnt vmcnt(8)
	s_waitcnt lgkmcnt(0)
	s_barrier
	s_waitcnt lgkmcnt(0)
	v_mfma_f32_16x16x32_bf16 v[124:127], v[128:131], v[216:219], v[124:127]
	v_mfma_f32_16x16x32_bf16 v[120:123], v[170:173], v[216:219], v[120:123]
	v_mfma_f32_16x16x32_bf16 v[108:111], v[128:131], v[224:227], v[108:111]
	v_mfma_f32_16x16x32_bf16 v[104:107], v[170:173], v[224:227], v[104:107]
	v_mfma_f32_16x16x32_bf16 v[92:95], v[128:131], v[232:235], v[92:95]
	v_mfma_f32_16x16x32_bf16 v[88:91], v[170:173], v[232:235], v[88:91]
	v_mfma_f32_16x16x32_bf16 v[76:79], v[128:131], v[240:243], v[76:79]
	v_mfma_f32_16x16x32_bf16 v[72:75], v[170:173], v[240:243], v[72:75]
	v_mfma_f32_16x16x32_bf16 v[124:127], v[166:169], v[220:223], v[124:127]
	v_mfma_f32_16x16x32_bf16 v[120:123], v[174:177], v[220:223], v[120:123]
	v_mfma_f32_16x16x32_bf16 v[108:111], v[166:169], v[228:231], v[108:111]
	v_mfma_f32_16x16x32_bf16 v[104:107], v[174:177], v[228:231], v[104:107]
	v_mfma_f32_16x16x32_bf16 v[92:95], v[166:169], v[236:239], v[92:95]
	v_mfma_f32_16x16x32_bf16 v[88:91], v[174:177], v[236:239], v[88:91]
	v_mfma_f32_16x16x32_bf16 v[76:79], v[166:169], v[244:247], v[76:79]
	v_mfma_f32_16x16x32_bf16 v[72:75], v[174:177], v[244:247], v[72:75]
	v_mfma_f32_16x16x32_bf16 v[116:119], v[178:181], v[216:219], v[116:119]
	v_mfma_f32_16x16x32_bf16 v[112:115], v[208:211], v[216:219], v[112:115]
	v_mfma_f32_16x16x32_bf16 v[100:103], v[178:181], v[224:227], v[100:103]
	v_mfma_f32_16x16x32_bf16 v[96:99], v[208:211], v[224:227], v[96:99]
	v_mfma_f32_16x16x32_bf16 v[84:87], v[178:181], v[232:235], v[84:87]
	v_mfma_f32_16x16x32_bf16 v[80:83], v[208:211], v[232:235], v[80:83]
	v_mfma_f32_16x16x32_bf16 v[68:71], v[178:181], v[240:243], v[68:71]
	v_mfma_f32_16x16x32_bf16 v[64:67], v[208:211], v[240:243], v[64:67]
	v_mfma_f32_16x16x32_bf16 v[116:119], v[204:207], v[220:223], v[116:119]
	v_mfma_f32_16x16x32_bf16 v[112:115], v[212:215], v[220:223], v[112:115]
	v_mfma_f32_16x16x32_bf16 v[100:103], v[204:207], v[228:231], v[100:103]
	v_mfma_f32_16x16x32_bf16 v[96:99], v[212:215], v[228:231], v[96:99]
	v_mfma_f32_16x16x32_bf16 v[84:87], v[204:207], v[236:239], v[84:87]
	v_mfma_f32_16x16x32_bf16 v[80:83], v[212:215], v[236:239], v[80:83]
	v_mfma_f32_16x16x32_bf16 v[68:71], v[204:207], v[244:247], v[68:71]
	v_mfma_f32_16x16x32_bf16 v[64:67], v[212:215], v[244:247], v[64:67]
	s_barrier
	s_add_i32 s37, s37, s86
	v_lshl_add_u64 v[192:193], v[248:249], 0, s[48:49]
	s_mov_b32 m0, s37
	ds_read_b128 v[216:219], v155 offset:49152
	ds_read_b128 v[220:223], v155 offset:50176
	ds_read_b128 v[224:227], v155 offset:51200
	ds_read_b128 v[228:231], v155 offset:52224
	ds_read_b128 v[232:235], v155 offset:53248
	ds_read_b128 v[236:239], v155 offset:54272
	ds_read_b128 v[240:243], v155 offset:55296
	ds_read_b128 v[244:247], v155 offset:56320
	global_load_lds_dwordx4 v[192:193], off
	s_add_i32 m0, s37, 0x2000
	s_add_u32 s42, s42, 0x40080
	v_lshl_add_u64 v[192:193], v[250:251], 0, s[48:49]
	s_addc_u32 s43, s43, 0
	s_add_i32 s37, s38, s86
	global_load_lds_dwordx4 v[192:193], off
	v_lshl_add_u64 v[192:193], s[42:43], 0, v[134:135]
	s_mov_b32 m0, s37
	v_lshl_add_u64 v[190:191], v[190:191], 0, s[48:49]
	global_load_lds_dwordx4 v[192:193], off
	v_lshl_add_u64 v[192:193], s[42:43], 0, v[138:139]
	s_add_i32 m0, s37, 0x2000
	s_nop 0
	global_load_lds_dwordx4 v[192:193], off
	v_lshl_add_u64 v[192:193], v[252:253], 0, s[48:49]
	s_mov_b32 m0, s82
	s_nop 0
	global_load_lds_dwordx4 v[192:193], off
	s_mov_b32 m0, s83
	s_nop 0
	global_load_lds_dwordx4 v[190:191], off
	s_waitcnt vmcnt(8)
	s_waitcnt lgkmcnt(0)
	s_barrier
	s_waitcnt lgkmcnt(0)
	v_mfma_f32_16x16x32_bf16 v[60:63], v[128:131], v[216:219], v[60:63]
	v_mfma_f32_16x16x32_bf16 v[56:59], v[170:173], v[216:219], v[56:59]
	v_mfma_f32_16x16x32_bf16 v[44:47], v[128:131], v[224:227], v[44:47]
	v_mfma_f32_16x16x32_bf16 v[40:43], v[170:173], v[224:227], v[40:43]
	v_mfma_f32_16x16x32_bf16 v[28:31], v[128:131], v[232:235], v[28:31]
	v_mfma_f32_16x16x32_bf16 v[24:27], v[170:173], v[232:235], v[24:27]
	v_mfma_f32_16x16x32_bf16 v[12:15], v[128:131], v[240:243], v[12:15]
	v_mfma_f32_16x16x32_bf16 v[8:11], v[170:173], v[240:243], v[8:11]
	v_mfma_f32_16x16x32_bf16 v[60:63], v[166:169], v[220:223], v[60:63]
	v_mfma_f32_16x16x32_bf16 v[56:59], v[174:177], v[220:223], v[56:59]
	v_mfma_f32_16x16x32_bf16 v[44:47], v[166:169], v[228:231], v[44:47]
	v_mfma_f32_16x16x32_bf16 v[40:43], v[174:177], v[228:231], v[40:43]
	v_mfma_f32_16x16x32_bf16 v[28:31], v[166:169], v[236:239], v[28:31]
	v_mfma_f32_16x16x32_bf16 v[24:27], v[174:177], v[236:239], v[24:27]
	v_mfma_f32_16x16x32_bf16 v[12:15], v[166:169], v[244:247], v[12:15]
	v_mfma_f32_16x16x32_bf16 v[8:11], v[174:177], v[244:247], v[8:11]
	v_mfma_f32_16x16x32_bf16 v[52:55], v[178:181], v[216:219], v[52:55]
	v_mfma_f32_16x16x32_bf16 v[48:51], v[208:211], v[216:219], v[48:51]
	v_mfma_f32_16x16x32_bf16 v[36:39], v[178:181], v[224:227], v[36:39]
	v_mfma_f32_16x16x32_bf16 v[32:35], v[208:211], v[224:227], v[32:35]
	v_mfma_f32_16x16x32_bf16 v[20:23], v[178:181], v[232:235], v[20:23]
	v_mfma_f32_16x16x32_bf16 v[16:19], v[208:211], v[232:235], v[16:19]
	v_mfma_f32_16x16x32_bf16 v[4:7], v[178:181], v[240:243], v[4:7]
	v_mfma_f32_16x16x32_bf16 v[0:3], v[208:211], v[240:243], v[0:3]
	v_mfma_f32_16x16x32_bf16 v[52:55], v[204:207], v[220:223], v[52:55]
	v_mfma_f32_16x16x32_bf16 v[48:51], v[212:215], v[220:223], v[48:51]
	v_mfma_f32_16x16x32_bf16 v[36:39], v[204:207], v[228:231], v[36:39]
	v_mfma_f32_16x16x32_bf16 v[32:35], v[212:215], v[228:231], v[32:35]
	v_mfma_f32_16x16x32_bf16 v[20:23], v[204:207], v[236:239], v[20:23]
	v_mfma_f32_16x16x32_bf16 v[16:19], v[212:215], v[236:239], v[16:19]
	v_mfma_f32_16x16x32_bf16 v[4:7], v[204:207], v[244:247], v[4:7]
	v_mfma_f32_16x16x32_bf16 v[0:3], v[212:215], v[244:247], v[0:3]
	s_barrier
	s_add_i32 s36, s36, 2
	s_add_u32 s4, s4, 0x100
	s_addc_u32 s5, s5, 0
	s_add_u32 s30, s30, 0x100
	s_addc_u32 s31, s31, 0
	s_cmp_gt_u32 s36, 13
	s_cbranch_scc0 .LBB0_594
	s_and_b64 vcc, exec, s[20:21]
	s_cbranch_vccz .LBB0_597
	s_barrier

.LBB0_979:
	s_add_u32 s12, s33, s10
	s_addc_u32 s13, s36, s11
	s_add_u32 s12, s12, 0x200100
	s_addc_u32 s13, s13, 0
	s_add_u32 s41, s37, s10
	s_addc_u32 s42, s38, s11
	s_add_i32 s43, 0, 0x10000
	s_cmpk_eq_i32 s10, 0xf00
	s_cselect_b32 s15, s9, s13
	s_cselect_b32 s14, s8, s12
	v_add_u32_e32 v142, s43, v140
	s_cselect_b32 s13, s7, s42
	s_cselect_b32 s12, s6, s41
	s_add_i32 s41, 0, 0x14000
	ds_read_b128 v[154:157], v142
	ds_read_b128 v[158:161], v142 offset:1024
	ds_read_b128 v[162:165], v142 offset:2048
	ds_read_b128 v[168:171], v142 offset:3072
	v_add_u32_e32 v142, s41, v140
	ds_read_b128 v[172:175], v142
	ds_read_b128 v[176:179], v142 offset:1024
	ds_read_b128 v[204:207], v142 offset:2048
	ds_read_b128 v[208:211], v142 offset:3072
	v_lshl_add_u64 v[142:143], v[136:137], 0, s[10:11]
	s_add_i32 m0, s23, 0xc000
	ds_read_b128 v[212:215], v141
	ds_read_b128 v[216:219], v141 offset:1024
	ds_read_b128 v[220:223], v141 offset:2048
	ds_read_b128 v[224:227], v141 offset:3072
	ds_read_b128 v[228:231], v141 offset:4096
	ds_read_b128 v[232:235], v141 offset:5120
	ds_read_b128 v[236:239], v141 offset:6144
	ds_read_b128 v[240:243], v141 offset:7168
	global_load_lds_dwordx4 v[142:143], off
	v_lshl_add_u64 v[142:143], v[138:139], 0, s[10:11]
	s_add_i32 m0, s23, 0xe000
	s_nop 0
	global_load_lds_dwordx4 v[142:143], off
	s_waitcnt vmcnt(8)
	s_waitcnt lgkmcnt(0)
	s_barrier
	s_waitcnt lgkmcnt(0)
	v_mfma_f32_16x16x32_bf16 v[124:127], v[154:157], v[212:215], v[124:127]
	v_mfma_f32_16x16x32_bf16 v[120:123], v[162:165], v[212:215], v[120:123]
	v_mfma_f32_16x16x32_bf16 v[112:115], v[154:157], v[220:223], v[112:115]
	v_mfma_f32_16x16x32_bf16 v[104:107], v[162:165], v[220:223], v[104:107]
	v_mfma_f32_16x16x32_bf16 v[96:99], v[154:157], v[228:231], v[96:99]
	v_mfma_f32_16x16x32_bf16 v[88:91], v[162:165], v[228:231], v[88:91]
	v_mfma_f32_16x16x32_bf16 v[80:83], v[154:157], v[236:239], v[80:83]
	v_mfma_f32_16x16x32_bf16 v[72:75], v[162:165], v[236:239], v[72:75]
	v_mfma_f32_16x16x32_bf16 v[124:127], v[158:161], v[216:219], v[124:127]
	v_mfma_f32_16x16x32_bf16 v[120:123], v[168:171], v[216:219], v[120:123]
	v_mfma_f32_16x16x32_bf16 v[112:115], v[158:161], v[224:227], v[112:115]
	v_mfma_f32_16x16x32_bf16 v[104:107], v[168:171], v[224:227], v[104:107]
	v_mfma_f32_16x16x32_bf16 v[96:99], v[158:161], v[232:235], v[96:99]
	v_mfma_f32_16x16x32_bf16 v[88:91], v[168:171], v[232:235], v[88:91]
	v_mfma_f32_16x16x32_bf16 v[80:83], v[158:161], v[240:243], v[80:83]
	v_mfma_f32_16x16x32_bf16 v[72:75], v[168:171], v[240:243], v[72:75]
	v_mfma_f32_16x16x32_bf16 v[116:119], v[172:175], v[212:215], v[116:119]
	v_mfma_f32_16x16x32_bf16 v[108:111], v[204:207], v[212:215], v[108:111]
	v_mfma_f32_16x16x32_bf16 v[100:103], v[172:175], v[220:223], v[100:103]
	v_mfma_f32_16x16x32_bf16 v[92:95], v[204:207], v[220:223], v[92:95]
	v_mfma_f32_16x16x32_bf16 v[84:87], v[172:175], v[228:231], v[84:87]
	v_mfma_f32_16x16x32_bf16 v[76:79], v[204:207], v[228:231], v[76:79]
	v_mfma_f32_16x16x32_bf16 v[68:71], v[172:175], v[236:239], v[68:71]
	v_mfma_f32_16x16x32_bf16 v[64:67], v[204:207], v[236:239], v[64:67]
	v_mfma_f32_16x16x32_bf16 v[116:119], v[176:179], v[216:219], v[116:119]
	v_mfma_f32_16x16x32_bf16 v[108:111], v[208:211], v[216:219], v[108:111]
	v_mfma_f32_16x16x32_bf16 v[100:103], v[176:179], v[224:227], v[100:103]
	v_mfma_f32_16x16x32_bf16 v[92:95], v[208:211], v[224:227], v[92:95]
	v_mfma_f32_16x16x32_bf16 v[84:87], v[176:179], v[232:235], v[84:87]
	v_mfma_f32_16x16x32_bf16 v[76:79], v[208:211], v[232:235], v[76:79]
	v_mfma_f32_16x16x32_bf16 v[68:71], v[176:179], v[240:243], v[68:71]
	v_mfma_f32_16x16x32_bf16 v[64:67], v[208:211], v[240:243], v[64:67]
	s_barrier
	s_add_i32 s42, s43, s19
	v_lshl_add_u64 v[142:143], s[12:13], 0, v[144:145]
	s_mov_b32 m0, s42
	ds_read_b128 v[212:215], v141 offset:16384
	ds_read_b128 v[216:219], v141 offset:17408
	ds_read_b128 v[220:223], v141 offset:18432
	ds_read_b128 v[224:227], v141 offset:19456
	ds_read_b128 v[228:231], v141 offset:20480
	ds_read_b128 v[232:235], v141 offset:21504
	ds_read_b128 v[236:239], v141 offset:22528
	ds_read_b128 v[240:243], v141 offset:23552
	global_load_lds_dwordx4 v[142:143], off
	s_add_i32 m0, s42, 0x2000
	s_add_u32 s42, s12, 0x80000
	v_lshl_add_u64 v[180:181], s[12:13], 0, v[130:131]
	s_addc_u32 s43, s13, 0
	s_add_i32 s41, s41, s19
	global_load_lds_dwordx4 v[180:181], off
	v_lshl_add_u64 v[190:191], s[42:43], 0, v[144:145]
	s_mov_b32 m0, s41
	v_lshl_add_u64 v[192:193], s[14:15], 0, v[132:133]
	global_load_lds_dwordx4 v[190:191], off
	v_lshl_add_u64 v[190:191], s[42:43], 0, v[130:131]
	s_add_i32 m0, s41, 0x2000
	s_nop 0
	global_load_lds_dwordx4 v[190:191], off
	v_lshl_add_u64 v[190:191], s[14:15], 0, v[134:135]
	s_mov_b32 m0, s23
	s_nop 0
	global_load_lds_dwordx4 v[190:191], off
	s_mov_b32 m0, s24
	s_nop 0
	global_load_lds_dwordx4 v[192:193], off
	s_waitcnt vmcnt(8)
	s_waitcnt lgkmcnt(0)
	s_barrier
	s_waitcnt lgkmcnt(0)
	v_mfma_f32_16x16x32_bf16 v[60:63], v[154:157], v[212:215], v[60:63]
	v_mfma_f32_16x16x32_bf16 v[56:59], v[162:165], v[212:215], v[56:59]
	v_mfma_f32_16x16x32_bf16 v[52:55], v[154:157], v[220:223], v[52:55]
	v_mfma_f32_16x16x32_bf16 v[44:47], v[162:165], v[220:223], v[44:47]
	v_mfma_f32_16x16x32_bf16 v[36:39], v[154:157], v[228:231], v[36:39]
	v_mfma_f32_16x16x32_bf16 v[28:31], v[162:165], v[228:231], v[28:31]
	v_mfma_f32_16x16x32_bf16 v[20:23], v[154:157], v[236:239], v[20:23]
	v_mfma_f32_16x16x32_bf16 v[12:15], v[162:165], v[236:239], v[12:15]
	v_mfma_f32_16x16x32_bf16 v[60:63], v[158:161], v[216:219], v[60:63]
	v_mfma_f32_16x16x32_bf16 v[56:59], v[168:171], v[216:219], v[56:59]
	v_mfma_f32_16x16x32_bf16 v[52:55], v[158:161], v[224:227], v[52:55]
	v_mfma_f32_16x16x32_bf16 v[44:47], v[168:171], v[224:227], v[44:47]
	v_mfma_f32_16x16x32_bf16 v[36:39], v[158:161], v[232:235], v[36:39]
	v_mfma_f32_16x16x32_bf16 v[28:31], v[168:171], v[232:235], v[28:31]
	v_mfma_f32_16x16x32_bf16 v[20:23], v[158:161], v[240:243], v[20:23]
	v_mfma_f32_16x16x32_bf16 v[12:15], v[168:171], v[240:243], v[12:15]
	v_mfma_f32_16x16x32_bf16 v[48:51], v[172:175], v[212:215], v[48:51]
	v_mfma_f32_16x16x32_bf16 v[40:43], v[204:207], v[212:215], v[40:43]
	v_mfma_f32_16x16x32_bf16 v[32:35], v[172:175], v[220:223], v[32:35]
	v_mfma_f32_16x16x32_bf16 v[24:27], v[204:207], v[220:223], v[24:27]
	v_mfma_f32_16x16x32_bf16 v[16:19], v[172:175], v[228:231], v[16:19]
	v_mfma_f32_16x16x32_bf16 v[8:11], v[204:207], v[228:231], v[8:11]
	v_mfma_f32_16x16x32_bf16 v[4:7], v[172:175], v[236:239], v[4:7]
	v_mfma_f32_16x16x32_bf16 v[0:3], v[204:207], v[236:239], v[0:3]
	v_mfma_f32_16x16x32_bf16 v[48:51], v[176:179], v[216:219], v[48:51]
	v_mfma_f32_16x16x32_bf16 v[40:43], v[208:211], v[216:219], v[40:43]
	v_mfma_f32_16x16x32_bf16 v[32:35], v[176:179], v[224:227], v[32:35]
	v_mfma_f32_16x16x32_bf16 v[24:27], v[208:211], v[224:227], v[24:27]
	v_mfma_f32_16x16x32_bf16 v[16:19], v[176:179], v[232:235], v[16:19]
	v_mfma_f32_16x16x32_bf16 v[8:11], v[208:211], v[232:235], v[8:11]
	v_mfma_f32_16x16x32_bf16 v[4:7], v[176:179], v[240:243], v[4:7]
	v_mfma_f32_16x16x32_bf16 v[0:3], v[208:211], v[240:243], v[0:3]
	s_barrier
	s_add_i32 s41, 0, 0x18000
	v_add_u32_e32 v167, s41, v140
	s_add_i32 s42, 0, 0x1c000
	ds_read_b128 v[154:157], v167
	ds_read_b128 v[158:161], v167 offset:1024
	ds_read_b128 v[162:165], v167 offset:2048
	ds_read_b128 v[168:171], v167 offset:3072
	v_add_u32_e32 v167, s42, v140
	ds_read_b128 v[172:175], v167
	ds_read_b128 v[176:179], v167 offset:1024
	ds_read_b128 v[204:207], v167 offset:2048
	ds_read_b128 v[208:211], v167 offset:3072
	s_add_u32 s14, s14, 0x80000
	s_addc_u32 s15, s15, 0
	s_mov_b32 m0, s25
	v_lshl_add_u64 v[244:245], s[14:15], 0, v[134:135]
	ds_read_b128 v[212:215], v141 offset:32768
	ds_read_b128 v[216:219], v141 offset:33792
	ds_read_b128 v[220:223], v141 offset:34816
	ds_read_b128 v[224:227], v141 offset:35840
	ds_read_b128 v[228:231], v141 offset:36864
	ds_read_b128 v[232:235], v141 offset:37888
	ds_read_b128 v[236:239], v141 offset:38912
	ds_read_b128 v[240:243], v141 offset:39936
	global_load_lds_dwordx4 v[244:245], off
	v_lshl_add_u64 v[244:245], s[14:15], 0, v[132:133]
	s_mov_b32 m0, s26
	s_nop 0
	global_load_lds_dwordx4 v[244:245], off
	s_waitcnt vmcnt(8)
	s_waitcnt lgkmcnt(0)
	s_barrier
	s_waitcnt lgkmcnt(0)
	v_mfma_f32_16x16x32_bf16 v[124:127], v[154:157], v[212:215], v[124:127]
	v_mfma_f32_16x16x32_bf16 v[120:123], v[162:165], v[212:215], v[120:123]
	v_mfma_f32_16x16x32_bf16 v[112:115], v[154:157], v[220:223], v[112:115]
	v_mfma_f32_16x16x32_bf16 v[104:107], v[162:165], v[220:223], v[104:107]
	v_mfma_f32_16x16x32_bf16 v[96:99], v[154:157], v[228:231], v[96:99]
	v_mfma_f32_16x16x32_bf16 v[88:91], v[162:165], v[228:231], v[88:91]
	v_mfma_f32_16x16x32_bf16 v[80:83], v[154:157], v[236:239], v[80:83]
	v_mfma_f32_16x16x32_bf16 v[72:75], v[162:165], v[236:239], v[72:75]
	v_mfma_f32_16x16x32_bf16 v[124:127], v[158:161], v[216:219], v[124:127]
	v_mfma_f32_16x16x32_bf16 v[120:123], v[168:171], v[216:219], v[120:123]
	v_mfma_f32_16x16x32_bf16 v[112:115], v[158:161], v[224:227], v[112:115]
	v_mfma_f32_16x16x32_bf16 v[104:107], v[168:171], v[224:227], v[104:107]
	v_mfma_f32_16x16x32_bf16 v[96:99], v[158:161], v[232:235], v[96:99]
	v_mfma_f32_16x16x32_bf16 v[88:91], v[168:171], v[232:235], v[88:91]
	v_mfma_f32_16x16x32_bf16 v[80:83], v[158:161], v[240:243], v[80:83]
	v_mfma_f32_16x16x32_bf16 v[72:75], v[168:171], v[240:243], v[72:75]
	v_mfma_f32_16x16x32_bf16 v[116:119], v[172:175], v[212:215], v[116:119]
	v_mfma_f32_16x16x32_bf16 v[108:111], v[204:207], v[212:215], v[108:111]
	v_mfma_f32_16x16x32_bf16 v[100:103], v[172:175], v[220:223], v[100:103]
	v_mfma_f32_16x16x32_bf16 v[92:95], v[204:207], v[220:223], v[92:95]
	v_mfma_f32_16x16x32_bf16 v[84:87], v[172:175], v[228:231], v[84:87]
	v_mfma_f32_16x16x32_bf16 v[76:79], v[204:207], v[228:231], v[76:79]
	v_mfma_f32_16x16x32_bf16 v[68:71], v[172:175], v[236:239], v[68:71]
	v_mfma_f32_16x16x32_bf16 v[64:67], v[204:207], v[236:239], v[64:67]
	v_mfma_f32_16x16x32_bf16 v[116:119], v[176:179], v[216:219], v[116:119]
	v_mfma_f32_16x16x32_bf16 v[108:111], v[208:211], v[216:219], v[108:111]
	v_mfma_f32_16x16x32_bf16 v[100:103], v[176:179], v[224:227], v[100:103]
	v_mfma_f32_16x16x32_bf16 v[92:95], v[208:211], v[224:227], v[92:95]
	v_mfma_f32_16x16x32_bf16 v[84:87], v[176:179], v[232:235], v[84:87]
	v_mfma_f32_16x16x32_bf16 v[76:79], v[208:211], v[232:235], v[76:79]
	v_mfma_f32_16x16x32_bf16 v[68:71], v[176:179], v[240:243], v[68:71]
	v_mfma_f32_16x16x32_bf16 v[64:67], v[208:211], v[240:243], v[64:67]
	s_barrier
	s_add_i32 s14, s41, s19
	v_lshl_add_u64 v[142:143], v[142:143], 0, s[48:49]
	s_mov_b32 m0, s14
	ds_read_b128 v[212:215], v141 offset:49152
	ds_read_b128 v[216:219], v141 offset:50176
	ds_read_b128 v[220:223], v141 offset:51200
	ds_read_b128 v[224:227], v141 offset:52224
	ds_read_b128 v[228:231], v141 offset:53248
	ds_read_b128 v[232:235], v141 offset:54272
	ds_read_b128 v[236:239], v141 offset:55296
	ds_read_b128 v[240:243], v141 offset:56320
	global_load_lds_dwordx4 v[142:143], off
	s_add_i32 m0, s14, 0x2000
	s_add_u32 s12, s12, 0x80080
	v_lshl_add_u64 v[142:143], v[180:181], 0, s[48:49]
	s_addc_u32 s13, s13, 0
	s_add_i32 s14, s42, s19
	global_load_lds_dwordx4 v[142:143], off
	v_lshl_add_u64 v[142:143], s[12:13], 0, v[144:145]
	s_mov_b32 m0, s14
	s_nop 0
	global_load_lds_dwordx4 v[142:143], off
	v_lshl_add_u64 v[142:143], s[12:13], 0, v[130:131]
	s_add_i32 m0, s14, 0x2000
	s_nop 0
	global_load_lds_dwordx4 v[142:143], off
	v_lshl_add_u64 v[142:143], v[190:191], 0, s[48:49]
	s_mov_b32 m0, s30
	s_nop 0
	global_load_lds_dwordx4 v[142:143], off
	v_lshl_add_u64 v[142:143], v[192:193], 0, s[48:49]
	s_mov_b32 m0, s31
	s_nop 0
	global_load_lds_dwordx4 v[142:143], off
	s_waitcnt vmcnt(8)
	s_waitcnt lgkmcnt(0)
	s_barrier
	s_waitcnt lgkmcnt(0)
	v_mfma_f32_16x16x32_bf16 v[60:63], v[154:157], v[212:215], v[60:63]
	v_mfma_f32_16x16x32_bf16 v[56:59], v[162:165], v[212:215], v[56:59]
	v_mfma_f32_16x16x32_bf16 v[52:55], v[154:157], v[220:223], v[52:55]
	v_mfma_f32_16x16x32_bf16 v[44:47], v[162:165], v[220:223], v[44:47]
	v_mfma_f32_16x16x32_bf16 v[36:39], v[154:157], v[228:231], v[36:39]
	v_mfma_f32_16x16x32_bf16 v[28:31], v[162:165], v[228:231], v[28:31]
	v_mfma_f32_16x16x32_bf16 v[20:23], v[154:157], v[236:239], v[20:23]
	v_mfma_f32_16x16x32_bf16 v[12:15], v[162:165], v[236:239], v[12:15]
	v_mfma_f32_16x16x32_bf16 v[60:63], v[158:161], v[216:219], v[60:63]
	v_mfma_f32_16x16x32_bf16 v[56:59], v[168:171], v[216:219], v[56:59]
	v_mfma_f32_16x16x32_bf16 v[52:55], v[158:161], v[224:227], v[52:55]
	v_mfma_f32_16x16x32_bf16 v[44:47], v[168:171], v[224:227], v[44:47]
	v_mfma_f32_16x16x32_bf16 v[36:39], v[158:161], v[232:235], v[36:39]
	v_mfma_f32_16x16x32_bf16 v[28:31], v[168:171], v[232:235], v[28:31]
	v_mfma_f32_16x16x32_bf16 v[20:23], v[158:161], v[240:243], v[20:23]
	v_mfma_f32_16x16x32_bf16 v[12:15], v[168:171], v[240:243], v[12:15]
	v_mfma_f32_16x16x32_bf16 v[48:51], v[172:175], v[212:215], v[48:51]
	v_mfma_f32_16x16x32_bf16 v[40:43], v[204:207], v[212:215], v[40:43]
	v_mfma_f32_16x16x32_bf16 v[32:35], v[172:175], v[220:223], v[32:35]
	v_mfma_f32_16x16x32_bf16 v[24:27], v[204:207], v[220:223], v[24:27]
	v_mfma_f32_16x16x32_bf16 v[16:19], v[172:175], v[228:231], v[16:19]
	v_mfma_f32_16x16x32_bf16 v[8:11], v[204:207], v[228:231], v[8:11]
	v_mfma_f32_16x16x32_bf16 v[4:7], v[172:175], v[236:239], v[4:7]
	v_mfma_f32_16x16x32_bf16 v[0:3], v[204:207], v[236:239], v[0:3]
	v_mfma_f32_16x16x32_bf16 v[48:51], v[176:179], v[216:219], v[48:51]
	v_mfma_f32_16x16x32_bf16 v[40:43], v[208:211], v[216:219], v[40:43]
	v_mfma_f32_16x16x32_bf16 v[32:35], v[176:179], v[224:227], v[32:35]
	v_mfma_f32_16x16x32_bf16 v[24:27], v[208:211], v[224:227], v[24:27]
	v_mfma_f32_16x16x32_bf16 v[16:19], v[176:179], v[232:235], v[16:19]
	v_mfma_f32_16x16x32_bf16 v[8:11], v[208:211], v[232:235], v[8:11]
	v_mfma_f32_16x16x32_bf16 v[4:7], v[176:179], v[240:243], v[4:7]
	v_mfma_f32_16x16x32_bf16 v[0:3], v[208:211], v[240:243], v[0:3]
	s_barrier
	s_add_i32 s40, s40, 2
	s_add_u32 s10, s10, 0x100
	s_addc_u32 s11, s11, 0
	s_cmp_gt_u32 s40, 29
	s_cbranch_scc0 .LBB0_979
	s_cmpk_lt_u32 s18, 0x100
	s_cbranch_scc0 .LBB0_982
	s_barrier

.LBB0_987:
	s_add_u32 s14, s12, 0x600100
	s_addc_u32 s15, s13, 0
	s_add_u32 s40, s12, s33
	s_addc_u32 s41, s13, s36
	s_add_i32 s42, 0, 0x10000
	s_cmp_eq_u32 s37, 4
	s_cselect_b32 s19, s9, s15
	s_cselect_b32 s18, s8, s14
	v_add_u32_e32 v142, s42, v140
	s_cselect_b32 s15, s11, s41
	s_cselect_b32 s14, s10, s40
	s_add_i32 s43, 0, 0x14000
	ds_read_b128 v[154:157], v142
	ds_read_b128 v[158:161], v142 offset:1024
	ds_read_b128 v[162:165], v142 offset:2048
	ds_read_b128 v[168:171], v142 offset:3072
	v_add_u32_e32 v142, s43, v140
	ds_read_b128 v[172:175], v142
	ds_read_b128 v[176:179], v142 offset:1024
	ds_read_b128 v[204:207], v142 offset:2048
	ds_read_b128 v[208:211], v142 offset:3072
	v_lshl_add_u64 v[142:143], s[12:13], 0, v[136:137]
	s_add_i32 m0, s23, 0xc000
	ds_read_b128 v[212:215], v141
	ds_read_b128 v[216:219], v141 offset:1024
	ds_read_b128 v[220:223], v141 offset:2048
	ds_read_b128 v[224:227], v141 offset:3072
	ds_read_b128 v[228:231], v141 offset:4096
	ds_read_b128 v[232:235], v141 offset:5120
	ds_read_b128 v[236:239], v141 offset:6144
	ds_read_b128 v[240:243], v141 offset:7168
	global_load_lds_dwordx4 v[142:143], off
	v_lshl_add_u64 v[142:143], s[12:13], 0, v[138:139]
	s_add_i32 m0, s23, 0xe000
	s_nop 0
	global_load_lds_dwordx4 v[142:143], off
	s_waitcnt vmcnt(8)
	s_waitcnt lgkmcnt(0)
	s_barrier
	s_waitcnt lgkmcnt(0)
	v_mfma_f32_16x16x32_bf16 v[124:127], v[154:157], v[212:215], v[124:127]
	v_mfma_f32_16x16x32_bf16 v[120:123], v[162:165], v[212:215], v[120:123]
	v_mfma_f32_16x16x32_bf16 v[112:115], v[154:157], v[220:223], v[112:115]
	v_mfma_f32_16x16x32_bf16 v[104:107], v[162:165], v[220:223], v[104:107]
	v_mfma_f32_16x16x32_bf16 v[96:99], v[154:157], v[228:231], v[96:99]
	v_mfma_f32_16x16x32_bf16 v[88:91], v[162:165], v[228:231], v[88:91]
	v_mfma_f32_16x16x32_bf16 v[80:83], v[154:157], v[236:239], v[80:83]
	v_mfma_f32_16x16x32_bf16 v[72:75], v[162:165], v[236:239], v[72:75]
	v_mfma_f32_16x16x32_bf16 v[124:127], v[158:161], v[216:219], v[124:127]
	v_mfma_f32_16x16x32_bf16 v[120:123], v[168:171], v[216:219], v[120:123]
	v_mfma_f32_16x16x32_bf16 v[112:115], v[158:161], v[224:227], v[112:115]
	v_mfma_f32_16x16x32_bf16 v[104:107], v[168:171], v[224:227], v[104:107]
	v_mfma_f32_16x16x32_bf16 v[96:99], v[158:161], v[232:235], v[96:99]
	v_mfma_f32_16x16x32_bf16 v[88:91], v[168:171], v[232:235], v[88:91]
	v_mfma_f32_16x16x32_bf16 v[80:83], v[158:161], v[240:243], v[80:83]
	v_mfma_f32_16x16x32_bf16 v[72:75], v[168:171], v[240:243], v[72:75]
	v_mfma_f32_16x16x32_bf16 v[116:119], v[172:175], v[212:215], v[116:119]
	v_mfma_f32_16x16x32_bf16 v[108:111], v[204:207], v[212:215], v[108:111]
	v_mfma_f32_16x16x32_bf16 v[100:103], v[172:175], v[220:223], v[100:103]
	v_mfma_f32_16x16x32_bf16 v[92:95], v[204:207], v[220:223], v[92:95]
	v_mfma_f32_16x16x32_bf16 v[84:87], v[172:175], v[228:231], v[84:87]
	v_mfma_f32_16x16x32_bf16 v[76:79], v[204:207], v[228:231], v[76:79]
	v_mfma_f32_16x16x32_bf16 v[68:71], v[172:175], v[236:239], v[68:71]
	v_mfma_f32_16x16x32_bf16 v[64:67], v[204:207], v[236:239], v[64:67]
	v_mfma_f32_16x16x32_bf16 v[116:119], v[176:179], v[216:219], v[116:119]
	v_mfma_f32_16x16x32_bf16 v[108:111], v[208:211], v[216:219], v[108:111]
	v_mfma_f32_16x16x32_bf16 v[100:103], v[176:179], v[224:227], v[100:103]
	v_mfma_f32_16x16x32_bf16 v[92:95], v[208:211], v[224:227], v[92:95]
	v_mfma_f32_16x16x32_bf16 v[84:87], v[176:179], v[232:235], v[84:87]
	v_mfma_f32_16x16x32_bf16 v[76:79], v[208:211], v[232:235], v[76:79]
	v_mfma_f32_16x16x32_bf16 v[68:71], v[176:179], v[240:243], v[68:71]
	v_mfma_f32_16x16x32_bf16 v[64:67], v[208:211], v[240:243], v[64:67]
	s_barrier
	s_add_i32 s40, s42, s22
	v_lshl_add_u64 v[142:143], s[14:15], 0, v[144:145]
	s_mov_b32 m0, s40
	ds_read_b128 v[212:215], v141 offset:16384
	ds_read_b128 v[216:219], v141 offset:17408
	ds_read_b128 v[220:223], v141 offset:18432
	ds_read_b128 v[224:227], v141 offset:19456
	ds_read_b128 v[228:231], v141 offset:20480
	ds_read_b128 v[232:235], v141 offset:21504
	ds_read_b128 v[236:239], v141 offset:22528
	ds_read_b128 v[240:243], v141 offset:23552
	global_load_lds_dwordx4 v[142:143], off
	s_add_i32 m0, s40, 0x2000
	s_add_u32 s40, s14, 0x20000
	v_lshl_add_u64 v[180:181], s[14:15], 0, v[130:131]
	s_addc_u32 s41, s15, 0
	s_add_i32 s42, s43, s22
	global_load_lds_dwordx4 v[180:181], off
	v_lshl_add_u64 v[190:191], s[40:41], 0, v[144:145]
	s_mov_b32 m0, s42
	v_lshl_add_u64 v[192:193], s[18:19], 0, v[132:133]
	global_load_lds_dwordx4 v[190:191], off
	v_lshl_add_u64 v[190:191], s[40:41], 0, v[130:131]
	s_add_i32 m0, s42, 0x2000
	s_nop 0
	global_load_lds_dwordx4 v[190:191], off
	v_lshl_add_u64 v[190:191], s[18:19], 0, v[134:135]
	s_mov_b32 m0, s23
	s_nop 0
	global_load_lds_dwordx4 v[190:191], off
	s_mov_b32 m0, s24
	s_nop 0
	global_load_lds_dwordx4 v[192:193], off
	s_waitcnt vmcnt(8)
	s_waitcnt lgkmcnt(0)
	s_barrier
	s_waitcnt lgkmcnt(0)
	v_mfma_f32_16x16x32_bf16 v[60:63], v[154:157], v[212:215], v[60:63]
	v_mfma_f32_16x16x32_bf16 v[56:59], v[162:165], v[212:215], v[56:59]
	v_mfma_f32_16x16x32_bf16 v[52:55], v[154:157], v[220:223], v[52:55]
	v_mfma_f32_16x16x32_bf16 v[44:47], v[162:165], v[220:223], v[44:47]
	v_mfma_f32_16x16x32_bf16 v[36:39], v[154:157], v[228:231], v[36:39]
	v_mfma_f32_16x16x32_bf16 v[28:31], v[162:165], v[228:231], v[28:31]
	v_mfma_f32_16x16x32_bf16 v[20:23], v[154:157], v[236:239], v[20:23]
	v_mfma_f32_16x16x32_bf16 v[12:15], v[162:165], v[236:239], v[12:15]
	v_mfma_f32_16x16x32_bf16 v[60:63], v[158:161], v[216:219], v[60:63]
	v_mfma_f32_16x16x32_bf16 v[56:59], v[168:171], v[216:219], v[56:59]
	v_mfma_f32_16x16x32_bf16 v[52:55], v[158:161], v[224:227], v[52:55]
	v_mfma_f32_16x16x32_bf16 v[44:47], v[168:171], v[224:227], v[44:47]
	v_mfma_f32_16x16x32_bf16 v[36:39], v[158:161], v[232:235], v[36:39]
	v_mfma_f32_16x16x32_bf16 v[28:31], v[168:171], v[232:235], v[28:31]
	v_mfma_f32_16x16x32_bf16 v[20:23], v[158:161], v[240:243], v[20:23]
	v_mfma_f32_16x16x32_bf16 v[12:15], v[168:171], v[240:243], v[12:15]
	v_mfma_f32_16x16x32_bf16 v[48:51], v[172:175], v[212:215], v[48:51]
	v_mfma_f32_16x16x32_bf16 v[40:43], v[204:207], v[212:215], v[40:43]
	v_mfma_f32_16x16x32_bf16 v[32:35], v[172:175], v[220:223], v[32:35]
	v_mfma_f32_16x16x32_bf16 v[24:27], v[204:207], v[220:223], v[24:27]
	v_mfma_f32_16x16x32_bf16 v[16:19], v[172:175], v[228:231], v[16:19]
	v_mfma_f32_16x16x32_bf16 v[8:11], v[204:207], v[228:231], v[8:11]
	v_mfma_f32_16x16x32_bf16 v[4:7], v[172:175], v[236:239], v[4:7]
	v_mfma_f32_16x16x32_bf16 v[0:3], v[204:207], v[236:239], v[0:3]
	v_mfma_f32_16x16x32_bf16 v[48:51], v[176:179], v[216:219], v[48:51]
	v_mfma_f32_16x16x32_bf16 v[40:43], v[208:211], v[216:219], v[40:43]
	v_mfma_f32_16x16x32_bf16 v[32:35], v[176:179], v[224:227], v[32:35]
	v_mfma_f32_16x16x32_bf16 v[24:27], v[208:211], v[224:227], v[24:27]
	v_mfma_f32_16x16x32_bf16 v[16:19], v[176:179], v[232:235], v[16:19]
	v_mfma_f32_16x16x32_bf16 v[8:11], v[208:211], v[232:235], v[8:11]
	v_mfma_f32_16x16x32_bf16 v[4:7], v[176:179], v[240:243], v[4:7]
	v_mfma_f32_16x16x32_bf16 v[0:3], v[208:211], v[240:243], v[0:3]
	s_barrier
	s_add_i32 s40, 0, 0x18000
	v_add_u32_e32 v167, s40, v140
	s_add_i32 s41, 0, 0x1c000
	ds_read_b128 v[154:157], v167
	ds_read_b128 v[158:161], v167 offset:1024
	ds_read_b128 v[162:165], v167 offset:2048
	ds_read_b128 v[168:171], v167 offset:3072
	v_add_u32_e32 v167, s41, v140
	ds_read_b128 v[172:175], v167
	ds_read_b128 v[176:179], v167 offset:1024
	ds_read_b128 v[204:207], v167 offset:2048
	ds_read_b128 v[208:211], v167 offset:3072
	s_add_u32 s18, s18, 0x20000
	s_addc_u32 s19, s19, 0
	s_mov_b32 m0, s25
	v_lshl_add_u64 v[244:245], s[18:19], 0, v[134:135]
	ds_read_b128 v[212:215], v141 offset:32768
	ds_read_b128 v[216:219], v141 offset:33792
	ds_read_b128 v[220:223], v141 offset:34816
	ds_read_b128 v[224:227], v141 offset:35840
	ds_read_b128 v[228:231], v141 offset:36864
	ds_read_b128 v[232:235], v141 offset:37888
	ds_read_b128 v[236:239], v141 offset:38912
	ds_read_b128 v[240:243], v141 offset:39936
	global_load_lds_dwordx4 v[244:245], off
	v_lshl_add_u64 v[244:245], s[18:19], 0, v[132:133]
	s_mov_b32 m0, s26
	s_nop 0
	global_load_lds_dwordx4 v[244:245], off
	s_waitcnt vmcnt(8)
	s_waitcnt lgkmcnt(0)
	s_barrier
	s_waitcnt lgkmcnt(0)
	v_mfma_f32_16x16x32_bf16 v[124:127], v[154:157], v[212:215], v[124:127]
	v_mfma_f32_16x16x32_bf16 v[120:123], v[162:165], v[212:215], v[120:123]
	v_mfma_f32_16x16x32_bf16 v[112:115], v[154:157], v[220:223], v[112:115]
	v_mfma_f32_16x16x32_bf16 v[104:107], v[162:165], v[220:223], v[104:107]
	v_mfma_f32_16x16x32_bf16 v[96:99], v[154:157], v[228:231], v[96:99]
	v_mfma_f32_16x16x32_bf16 v[88:91], v[162:165], v[228:231], v[88:91]
	v_mfma_f32_16x16x32_bf16 v[80:83], v[154:157], v[236:239], v[80:83]
	v_mfma_f32_16x16x32_bf16 v[72:75], v[162:165], v[236:239], v[72:75]
	v_mfma_f32_16x16x32_bf16 v[124:127], v[158:161], v[216:219], v[124:127]
	v_mfma_f32_16x16x32_bf16 v[120:123], v[168:171], v[216:219], v[120:123]
	v_mfma_f32_16x16x32_bf16 v[112:115], v[158:161], v[224:227], v[112:115]
	v_mfma_f32_16x16x32_bf16 v[104:107], v[168:171], v[224:227], v[104:107]
	v_mfma_f32_16x16x32_bf16 v[96:99], v[158:161], v[232:235], v[96:99]
	v_mfma_f32_16x16x32_bf16 v[88:91], v[168:171], v[232:235], v[88:91]
	v_mfma_f32_16x16x32_bf16 v[80:83], v[158:161], v[240:243], v[80:83]
	v_mfma_f32_16x16x32_bf16 v[72:75], v[168:171], v[240:243], v[72:75]
	v_mfma_f32_16x16x32_bf16 v[116:119], v[172:175], v[212:215], v[116:119]
	v_mfma_f32_16x16x32_bf16 v[108:111], v[204:207], v[212:215], v[108:111]
	v_mfma_f32_16x16x32_bf16 v[100:103], v[172:175], v[220:223], v[100:103]
	v_mfma_f32_16x16x32_bf16 v[92:95], v[204:207], v[220:223], v[92:95]
	v_mfma_f32_16x16x32_bf16 v[84:87], v[172:175], v[228:231], v[84:87]
	v_mfma_f32_16x16x32_bf16 v[76:79], v[204:207], v[228:231], v[76:79]
	v_mfma_f32_16x16x32_bf16 v[68:71], v[172:175], v[236:239], v[68:71]
	v_mfma_f32_16x16x32_bf16 v[64:67], v[204:207], v[236:239], v[64:67]
	v_mfma_f32_16x16x32_bf16 v[116:119], v[176:179], v[216:219], v[116:119]
	v_mfma_f32_16x16x32_bf16 v[108:111], v[208:211], v[216:219], v[108:111]
	v_mfma_f32_16x16x32_bf16 v[100:103], v[176:179], v[224:227], v[100:103]
	v_mfma_f32_16x16x32_bf16 v[92:95], v[208:211], v[224:227], v[92:95]
	v_mfma_f32_16x16x32_bf16 v[84:87], v[176:179], v[232:235], v[84:87]
	v_mfma_f32_16x16x32_bf16 v[76:79], v[208:211], v[232:235], v[76:79]
	v_mfma_f32_16x16x32_bf16 v[68:71], v[176:179], v[240:243], v[68:71]
	v_mfma_f32_16x16x32_bf16 v[64:67], v[208:211], v[240:243], v[64:67]
	s_barrier
	s_add_i32 s18, s40, s22
	v_lshl_add_u64 v[142:143], v[142:143], 0, s[48:49]
	s_mov_b32 m0, s18
	ds_read_b128 v[212:215], v141 offset:49152
	ds_read_b128 v[216:219], v141 offset:50176
	ds_read_b128 v[220:223], v141 offset:51200
	ds_read_b128 v[224:227], v141 offset:52224
	ds_read_b128 v[228:231], v141 offset:53248
	ds_read_b128 v[232:235], v141 offset:54272
	ds_read_b128 v[236:239], v141 offset:55296
	ds_read_b128 v[240:243], v141 offset:56320
	global_load_lds_dwordx4 v[142:143], off
	s_add_i32 m0, s18, 0x2000
	s_add_u32 s14, s14, 0x20080
	v_lshl_add_u64 v[142:143], v[180:181], 0, s[48:49]
	s_addc_u32 s15, s15, 0
	s_add_i32 s18, s41, s22
	global_load_lds_dwordx4 v[142:143], off
	v_lshl_add_u64 v[142:143], s[14:15], 0, v[144:145]
	s_mov_b32 m0, s18
	s_nop 0
	global_load_lds_dwordx4 v[142:143], off
	v_lshl_add_u64 v[142:143], s[14:15], 0, v[130:131]
	s_add_i32 m0, s18, 0x2000
	s_nop 0
	global_load_lds_dwordx4 v[142:143], off
	v_lshl_add_u64 v[142:143], v[190:191], 0, s[48:49]
	s_mov_b32 m0, s30
	s_nop 0
	global_load_lds_dwordx4 v[142:143], off
	v_lshl_add_u64 v[142:143], v[192:193], 0, s[48:49]
	s_mov_b32 m0, s31
	s_nop 0
	global_load_lds_dwordx4 v[142:143], off
	s_waitcnt vmcnt(8)
	s_waitcnt lgkmcnt(0)
	s_barrier
	s_waitcnt lgkmcnt(0)
	v_mfma_f32_16x16x32_bf16 v[60:63], v[154:157], v[212:215], v[60:63]
	v_mfma_f32_16x16x32_bf16 v[56:59], v[162:165], v[212:215], v[56:59]
	v_mfma_f32_16x16x32_bf16 v[52:55], v[154:157], v[220:223], v[52:55]
	v_mfma_f32_16x16x32_bf16 v[44:47], v[162:165], v[220:223], v[44:47]
	v_mfma_f32_16x16x32_bf16 v[36:39], v[154:157], v[228:231], v[36:39]
	v_mfma_f32_16x16x32_bf16 v[28:31], v[162:165], v[228:231], v[28:31]
	v_mfma_f32_16x16x32_bf16 v[20:23], v[154:157], v[236:239], v[20:23]
	v_mfma_f32_16x16x32_bf16 v[12:15], v[162:165], v[236:239], v[12:15]
	v_mfma_f32_16x16x32_bf16 v[60:63], v[158:161], v[216:219], v[60:63]
	v_mfma_f32_16x16x32_bf16 v[56:59], v[168:171], v[216:219], v[56:59]
	v_mfma_f32_16x16x32_bf16 v[52:55], v[158:161], v[224:227], v[52:55]
	v_mfma_f32_16x16x32_bf16 v[44:47], v[168:171], v[224:227], v[44:47]
	v_mfma_f32_16x16x32_bf16 v[36:39], v[158:161], v[232:235], v[36:39]
	v_mfma_f32_16x16x32_bf16 v[28:31], v[168:171], v[232:235], v[28:31]
	v_mfma_f32_16x16x32_bf16 v[20:23], v[158:161], v[240:243], v[20:23]
	v_mfma_f32_16x16x32_bf16 v[12:15], v[168:171], v[240:243], v[12:15]
	v_mfma_f32_16x16x32_bf16 v[48:51], v[172:175], v[212:215], v[48:51]
	v_mfma_f32_16x16x32_bf16 v[40:43], v[204:207], v[212:215], v[40:43]
	v_mfma_f32_16x16x32_bf16 v[32:35], v[172:175], v[220:223], v[32:35]
	v_mfma_f32_16x16x32_bf16 v[24:27], v[204:207], v[220:223], v[24:27]
	v_mfma_f32_16x16x32_bf16 v[16:19], v[172:175], v[228:231], v[16:19]
	v_mfma_f32_16x16x32_bf16 v[8:11], v[204:207], v[228:231], v[8:11]
	v_mfma_f32_16x16x32_bf16 v[4:7], v[172:175], v[236:239], v[4:7]
	v_mfma_f32_16x16x32_bf16 v[0:3], v[204:207], v[236:239], v[0:3]
	v_mfma_f32_16x16x32_bf16 v[48:51], v[176:179], v[216:219], v[48:51]
	v_mfma_f32_16x16x32_bf16 v[40:43], v[208:211], v[216:219], v[40:43]
	v_mfma_f32_16x16x32_bf16 v[32:35], v[176:179], v[224:227], v[32:35]
	v_mfma_f32_16x16x32_bf16 v[24:27], v[208:211], v[224:227], v[24:27]
	v_mfma_f32_16x16x32_bf16 v[16:19], v[176:179], v[232:235], v[16:19]
	v_mfma_f32_16x16x32_bf16 v[8:11], v[208:211], v[232:235], v[8:11]
	v_mfma_f32_16x16x32_bf16 v[4:7], v[176:179], v[240:243], v[4:7]
	v_mfma_f32_16x16x32_bf16 v[0:3], v[208:211], v[240:243], v[0:3]
	s_barrier
	s_add_i32 s37, s37, 2
	s_add_u32 s12, s12, 0x100
	s_addc_u32 s13, s13, 0
	s_cmp_gt_u32 s37, 5
	s_cbranch_scc0 .LBB0_987
	s_cmpk_lt_u32 s21, 0x100
	s_cbranch_scc0 .LBB0_990
	s_barrier

.LBB0_997:
	s_add_u32 s12, s31, s10
	s_addc_u32 s13, s33, s11
	s_add_u32 s12, s12, 0x1000100
	s_addc_u32 s13, s13, 0
	s_add_u32 s41, s36, s10
	s_addc_u32 s42, s37, s11
	s_add_i32 s43, 0, 0x10000
	s_cmpk_eq_i32 s10, 0x700
	s_cselect_b32 s15, s9, s13
	s_cselect_b32 s14, s8, s12
	v_add_u32_e32 v143, s43, v141
	s_cselect_b32 s13, s7, s42
	s_cselect_b32 s12, s6, s41
	s_add_i32 s41, 0, 0x14000
	ds_read_b128 v[154:157], v143
	ds_read_b128 v[158:161], v143 offset:1024
	ds_read_b128 v[162:165], v143 offset:2048
	ds_read_b128 v[168:171], v143 offset:3072
	v_add_u32_e32 v143, s41, v141
	ds_read_b128 v[172:175], v143
	ds_read_b128 v[176:179], v143 offset:1024
	ds_read_b128 v[204:207], v143 offset:2048
	ds_read_b128 v[208:211], v143 offset:3072
	v_lshl_add_u64 v[180:181], v[136:137], 0, s[10:11]
	s_add_i32 m0, s21, 0xc000
	ds_read_b128 v[212:215], v142
	ds_read_b128 v[216:219], v142 offset:1024
	ds_read_b128 v[220:223], v142 offset:2048
	ds_read_b128 v[224:227], v142 offset:3072
	ds_read_b128 v[228:231], v142 offset:4096
	ds_read_b128 v[232:235], v142 offset:5120
	ds_read_b128 v[236:239], v142 offset:6144
	ds_read_b128 v[240:243], v142 offset:7168
	global_load_lds_dwordx4 v[180:181], off
	v_lshl_add_u64 v[180:181], v[138:139], 0, s[10:11]
	s_add_i32 m0, s21, 0xe000
	s_nop 0
	global_load_lds_dwordx4 v[180:181], off
	s_waitcnt vmcnt(8)
	s_waitcnt lgkmcnt(0)
	s_barrier
	s_waitcnt lgkmcnt(0)
	v_mfma_f32_16x16x32_bf16 v[124:127], v[154:157], v[212:215], v[124:127]
	v_mfma_f32_16x16x32_bf16 v[120:123], v[162:165], v[212:215], v[120:123]
	v_mfma_f32_16x16x32_bf16 v[108:111], v[154:157], v[220:223], v[108:111]
	v_mfma_f32_16x16x32_bf16 v[104:107], v[162:165], v[220:223], v[104:107]
	v_mfma_f32_16x16x32_bf16 v[92:95], v[154:157], v[228:231], v[92:95]
	v_mfma_f32_16x16x32_bf16 v[88:91], v[162:165], v[228:231], v[88:91]
	v_mfma_f32_16x16x32_bf16 v[76:79], v[154:157], v[236:239], v[76:79]
	v_mfma_f32_16x16x32_bf16 v[72:75], v[162:165], v[236:239], v[72:75]
	v_mfma_f32_16x16x32_bf16 v[124:127], v[158:161], v[216:219], v[124:127]
	v_mfma_f32_16x16x32_bf16 v[120:123], v[168:171], v[216:219], v[120:123]
	v_mfma_f32_16x16x32_bf16 v[108:111], v[158:161], v[224:227], v[108:111]
	v_mfma_f32_16x16x32_bf16 v[104:107], v[168:171], v[224:227], v[104:107]
	v_mfma_f32_16x16x32_bf16 v[92:95], v[158:161], v[232:235], v[92:95]
	v_mfma_f32_16x16x32_bf16 v[88:91], v[168:171], v[232:235], v[88:91]
	v_mfma_f32_16x16x32_bf16 v[76:79], v[158:161], v[240:243], v[76:79]
	v_mfma_f32_16x16x32_bf16 v[72:75], v[168:171], v[240:243], v[72:75]
	v_mfma_f32_16x16x32_bf16 v[116:119], v[172:175], v[212:215], v[116:119]
	v_mfma_f32_16x16x32_bf16 v[112:115], v[204:207], v[212:215], v[112:115]
	v_mfma_f32_16x16x32_bf16 v[100:103], v[172:175], v[220:223], v[100:103]
	v_mfma_f32_16x16x32_bf16 v[96:99], v[204:207], v[220:223], v[96:99]
	v_mfma_f32_16x16x32_bf16 v[84:87], v[172:175], v[228:231], v[84:87]
	v_mfma_f32_16x16x32_bf16 v[80:83], v[204:207], v[228:231], v[80:83]
	v_mfma_f32_16x16x32_bf16 v[68:71], v[172:175], v[236:239], v[68:71]
	v_mfma_f32_16x16x32_bf16 v[64:67], v[204:207], v[236:239], v[64:67]
	v_mfma_f32_16x16x32_bf16 v[116:119], v[176:179], v[216:219], v[116:119]
	v_mfma_f32_16x16x32_bf16 v[112:115], v[208:211], v[216:219], v[112:115]
	v_mfma_f32_16x16x32_bf16 v[100:103], v[176:179], v[224:227], v[100:103]
	v_mfma_f32_16x16x32_bf16 v[96:99], v[208:211], v[224:227], v[96:99]
	v_mfma_f32_16x16x32_bf16 v[84:87], v[176:179], v[232:235], v[84:87]
	v_mfma_f32_16x16x32_bf16 v[80:83], v[208:211], v[232:235], v[80:83]
	v_mfma_f32_16x16x32_bf16 v[68:71], v[176:179], v[240:243], v[68:71]
	v_mfma_f32_16x16x32_bf16 v[64:67], v[208:211], v[240:243], v[64:67]
	s_barrier
	s_add_i32 s42, s43, s19
	v_lshl_add_u64 v[180:181], s[12:13], 0, v[144:145]
	s_mov_b32 m0, s42
	ds_read_b128 v[212:215], v142 offset:16384
	ds_read_b128 v[216:219], v142 offset:17408
	ds_read_b128 v[220:223], v142 offset:18432
	ds_read_b128 v[224:227], v142 offset:19456
	ds_read_b128 v[228:231], v142 offset:20480
	ds_read_b128 v[232:235], v142 offset:21504
	ds_read_b128 v[236:239], v142 offset:22528
	ds_read_b128 v[240:243], v142 offset:23552
	global_load_lds_dwordx4 v[180:181], off
	s_add_i32 m0, s42, 0x2000
	s_add_u32 s42, s12, 0x40000
	v_lshl_add_u64 v[190:191], s[12:13], 0, v[130:131]
	s_addc_u32 s43, s13, 0
	s_add_i32 s41, s41, s19
	global_load_lds_dwordx4 v[190:191], off
	v_lshl_add_u64 v[192:193], s[42:43], 0, v[144:145]
	s_mov_b32 m0, s41
	v_lshl_add_u64 v[244:245], s[14:15], 0, v[132:133]
	global_load_lds_dwordx4 v[192:193], off
	v_lshl_add_u64 v[192:193], s[42:43], 0, v[130:131]
	s_add_i32 m0, s41, 0x2000
	s_nop 0
	global_load_lds_dwordx4 v[192:193], off
	v_lshl_add_u64 v[192:193], s[14:15], 0, v[134:135]
	s_mov_b32 m0, s21
	s_nop 0
	global_load_lds_dwordx4 v[192:193], off
	s_mov_b32 m0, s22
	s_nop 0
	global_load_lds_dwordx4 v[244:245], off
	s_waitcnt vmcnt(8)
	s_waitcnt lgkmcnt(0)
	s_barrier
	s_waitcnt lgkmcnt(0)
	v_mfma_f32_16x16x32_bf16 v[60:63], v[154:157], v[212:215], v[60:63]
	v_mfma_f32_16x16x32_bf16 v[56:59], v[162:165], v[212:215], v[56:59]
	v_mfma_f32_16x16x32_bf16 v[44:47], v[154:157], v[220:223], v[44:47]
	v_mfma_f32_16x16x32_bf16 v[40:43], v[162:165], v[220:223], v[40:43]
	v_mfma_f32_16x16x32_bf16 v[28:31], v[154:157], v[228:231], v[28:31]
	v_mfma_f32_16x16x32_bf16 v[24:27], v[162:165], v[228:231], v[24:27]
	v_mfma_f32_16x16x32_bf16 v[12:15], v[154:157], v[236:239], v[12:15]
	v_mfma_f32_16x16x32_bf16 v[8:11], v[162:165], v[236:239], v[8:11]
	v_mfma_f32_16x16x32_bf16 v[60:63], v[158:161], v[216:219], v[60:63]
	v_mfma_f32_16x16x32_bf16 v[56:59], v[168:171], v[216:219], v[56:59]
	v_mfma_f32_16x16x32_bf16 v[44:47], v[158:161], v[224:227], v[44:47]
	v_mfma_f32_16x16x32_bf16 v[40:43], v[168:171], v[224:227], v[40:43]
	v_mfma_f32_16x16x32_bf16 v[28:31], v[158:161], v[232:235], v[28:31]
	v_mfma_f32_16x16x32_bf16 v[24:27], v[168:171], v[232:235], v[24:27]
	v_mfma_f32_16x16x32_bf16 v[12:15], v[158:161], v[240:243], v[12:15]
	v_mfma_f32_16x16x32_bf16 v[8:11], v[168:171], v[240:243], v[8:11]
	v_mfma_f32_16x16x32_bf16 v[52:55], v[172:175], v[212:215], v[52:55]
	v_mfma_f32_16x16x32_bf16 v[48:51], v[204:207], v[212:215], v[48:51]
	v_mfma_f32_16x16x32_bf16 v[36:39], v[172:175], v[220:223], v[36:39]
	v_mfma_f32_16x16x32_bf16 v[32:35], v[204:207], v[220:223], v[32:35]
	v_mfma_f32_16x16x32_bf16 v[20:23], v[172:175], v[228:231], v[20:23]
	v_mfma_f32_16x16x32_bf16 v[16:19], v[204:207], v[228:231], v[16:19]
	v_mfma_f32_16x16x32_bf16 v[4:7], v[172:175], v[236:239], v[4:7]
	v_mfma_f32_16x16x32_bf16 v[0:3], v[204:207], v[236:239], v[0:3]
	v_mfma_f32_16x16x32_bf16 v[52:55], v[176:179], v[216:219], v[52:55]
	v_mfma_f32_16x16x32_bf16 v[48:51], v[208:211], v[216:219], v[48:51]
	v_mfma_f32_16x16x32_bf16 v[36:39], v[176:179], v[224:227], v[36:39]
	v_mfma_f32_16x16x32_bf16 v[32:35], v[208:211], v[224:227], v[32:35]
	v_mfma_f32_16x16x32_bf16 v[20:23], v[176:179], v[232:235], v[20:23]
	v_mfma_f32_16x16x32_bf16 v[16:19], v[208:211], v[232:235], v[16:19]
	v_mfma_f32_16x16x32_bf16 v[4:7], v[176:179], v[240:243], v[4:7]
	v_mfma_f32_16x16x32_bf16 v[0:3], v[208:211], v[240:243], v[0:3]
	s_barrier
	s_add_i32 s41, 0, 0x18000
	v_add_u32_e32 v143, s41, v141
	s_add_i32 s42, 0, 0x1c000
	ds_read_b128 v[154:157], v143
	ds_read_b128 v[158:161], v143 offset:1024
	ds_read_b128 v[162:165], v143 offset:2048
	ds_read_b128 v[168:171], v143 offset:3072
	v_add_u32_e32 v143, s42, v141
	ds_read_b128 v[172:175], v143
	ds_read_b128 v[176:179], v143 offset:1024
	ds_read_b128 v[204:207], v143 offset:2048
	ds_read_b128 v[208:211], v143 offset:3072
	s_add_u32 s14, s14, 0x40000
	s_addc_u32 s15, s15, 0
	s_mov_b32 m0, s23
	v_lshl_add_u64 v[246:247], s[14:15], 0, v[134:135]
	ds_read_b128 v[212:215], v142 offset:32768
	ds_read_b128 v[216:219], v142 offset:33792
	ds_read_b128 v[220:223], v142 offset:34816
	ds_read_b128 v[224:227], v142 offset:35840
	ds_read_b128 v[228:231], v142 offset:36864
	ds_read_b128 v[232:235], v142 offset:37888
	ds_read_b128 v[236:239], v142 offset:38912
	ds_read_b128 v[240:243], v142 offset:39936
	global_load_lds_dwordx4 v[246:247], off
	v_lshl_add_u64 v[246:247], s[14:15], 0, v[132:133]
	s_mov_b32 m0, s25
	s_nop 0
	global_load_lds_dwordx4 v[246:247], off
	s_waitcnt vmcnt(8)
	s_waitcnt lgkmcnt(0)
	s_barrier
	s_waitcnt lgkmcnt(0)
	v_mfma_f32_16x16x32_bf16 v[124:127], v[154:157], v[212:215], v[124:127]
	v_mfma_f32_16x16x32_bf16 v[120:123], v[162:165], v[212:215], v[120:123]
	v_mfma_f32_16x16x32_bf16 v[108:111], v[154:157], v[220:223], v[108:111]
	v_mfma_f32_16x16x32_bf16 v[104:107], v[162:165], v[220:223], v[104:107]
	v_mfma_f32_16x16x32_bf16 v[92:95], v[154:157], v[228:231], v[92:95]
	v_mfma_f32_16x16x32_bf16 v[88:91], v[162:165], v[228:231], v[88:91]
	v_mfma_f32_16x16x32_bf16 v[76:79], v[154:157], v[236:239], v[76:79]
	v_mfma_f32_16x16x32_bf16 v[72:75], v[162:165], v[236:239], v[72:75]
	v_mfma_f32_16x16x32_bf16 v[124:127], v[158:161], v[216:219], v[124:127]
	v_mfma_f32_16x16x32_bf16 v[120:123], v[168:171], v[216:219], v[120:123]
	v_mfma_f32_16x16x32_bf16 v[108:111], v[158:161], v[224:227], v[108:111]
	v_mfma_f32_16x16x32_bf16 v[104:107], v[168:171], v[224:227], v[104:107]
	v_mfma_f32_16x16x32_bf16 v[92:95], v[158:161], v[232:235], v[92:95]
	v_mfma_f32_16x16x32_bf16 v[88:91], v[168:171], v[232:235], v[88:91]
	v_mfma_f32_16x16x32_bf16 v[76:79], v[158:161], v[240:243], v[76:79]
	v_mfma_f32_16x16x32_bf16 v[72:75], v[168:171], v[240:243], v[72:75]
	v_mfma_f32_16x16x32_bf16 v[116:119], v[172:175], v[212:215], v[116:119]
	v_mfma_f32_16x16x32_bf16 v[112:115], v[204:207], v[212:215], v[112:115]
	v_mfma_f32_16x16x32_bf16 v[100:103], v[172:175], v[220:223], v[100:103]
	v_mfma_f32_16x16x32_bf16 v[96:99], v[204:207], v[220:223], v[96:99]
	v_mfma_f32_16x16x32_bf16 v[84:87], v[172:175], v[228:231], v[84:87]
	v_mfma_f32_16x16x32_bf16 v[80:83], v[204:207], v[228:231], v[80:83]
	v_mfma_f32_16x16x32_bf16 v[68:71], v[172:175], v[236:239], v[68:71]
	v_mfma_f32_16x16x32_bf16 v[64:67], v[204:207], v[236:239], v[64:67]
	v_mfma_f32_16x16x32_bf16 v[116:119], v[176:179], v[216:219], v[116:119]
	v_mfma_f32_16x16x32_bf16 v[112:115], v[208:211], v[216:219], v[112:115]
	v_mfma_f32_16x16x32_bf16 v[100:103], v[176:179], v[224:227], v[100:103]
	v_mfma_f32_16x16x32_bf16 v[96:99], v[208:211], v[224:227], v[96:99]
	v_mfma_f32_16x16x32_bf16 v[84:87], v[176:179], v[232:235], v[84:87]
	v_mfma_f32_16x16x32_bf16 v[80:83], v[208:211], v[232:235], v[80:83]
	v_mfma_f32_16x16x32_bf16 v[68:71], v[176:179], v[240:243], v[68:71]
	v_mfma_f32_16x16x32_bf16 v[64:67], v[208:211], v[240:243], v[64:67]
	s_barrier
	s_add_i32 s14, s41, s19
	v_lshl_add_u64 v[180:181], v[180:181], 0, s[48:49]
	s_mov_b32 m0, s14
	ds_read_b128 v[212:215], v142 offset:49152
	ds_read_b128 v[216:219], v142 offset:50176
	ds_read_b128 v[220:223], v142 offset:51200
	ds_read_b128 v[224:227], v142 offset:52224
	ds_read_b128 v[228:231], v142 offset:53248
	ds_read_b128 v[232:235], v142 offset:54272
	ds_read_b128 v[236:239], v142 offset:55296
	ds_read_b128 v[240:243], v142 offset:56320
	global_load_lds_dwordx4 v[180:181], off
	s_add_i32 m0, s14, 0x2000
	s_add_u32 s12, s12, 0x40080
	v_lshl_add_u64 v[180:181], v[190:191], 0, s[48:49]
	s_addc_u32 s13, s13, 0
	s_add_i32 s14, s42, s19
	global_load_lds_dwordx4 v[180:181], off
	v_lshl_add_u64 v[180:181], s[12:13], 0, v[144:145]
	s_mov_b32 m0, s14
	s_nop 0
	global_load_lds_dwordx4 v[180:181], off
	v_lshl_add_u64 v[180:181], s[12:13], 0, v[130:131]
	s_add_i32 m0, s14, 0x2000
	s_nop 0
	global_load_lds_dwordx4 v[180:181], off
	v_lshl_add_u64 v[180:181], v[192:193], 0, s[48:49]
	s_mov_b32 m0, s27
	s_nop 0
	global_load_lds_dwordx4 v[180:181], off
	v_lshl_add_u64 v[180:181], v[244:245], 0, s[48:49]
	s_mov_b32 m0, s30
	s_nop 0
	global_load_lds_dwordx4 v[180:181], off
	s_waitcnt vmcnt(8)
	s_waitcnt lgkmcnt(0)
	s_barrier
	s_waitcnt lgkmcnt(0)
	v_mfma_f32_16x16x32_bf16 v[60:63], v[154:157], v[212:215], v[60:63]
	v_mfma_f32_16x16x32_bf16 v[56:59], v[162:165], v[212:215], v[56:59]
	v_mfma_f32_16x16x32_bf16 v[44:47], v[154:157], v[220:223], v[44:47]
	v_mfma_f32_16x16x32_bf16 v[40:43], v[162:165], v[220:223], v[40:43]
	v_mfma_f32_16x16x32_bf16 v[28:31], v[154:157], v[228:231], v[28:31]
	v_mfma_f32_16x16x32_bf16 v[24:27], v[162:165], v[228:231], v[24:27]
	v_mfma_f32_16x16x32_bf16 v[12:15], v[154:157], v[236:239], v[12:15]
	v_mfma_f32_16x16x32_bf16 v[8:11], v[162:165], v[236:239], v[8:11]
	v_mfma_f32_16x16x32_bf16 v[60:63], v[158:161], v[216:219], v[60:63]
	v_mfma_f32_16x16x32_bf16 v[56:59], v[168:171], v[216:219], v[56:59]
	v_mfma_f32_16x16x32_bf16 v[44:47], v[158:161], v[224:227], v[44:47]
	v_mfma_f32_16x16x32_bf16 v[40:43], v[168:171], v[224:227], v[40:43]
	v_mfma_f32_16x16x32_bf16 v[28:31], v[158:161], v[232:235], v[28:31]
	v_mfma_f32_16x16x32_bf16 v[24:27], v[168:171], v[232:235], v[24:27]
	v_mfma_f32_16x16x32_bf16 v[12:15], v[158:161], v[240:243], v[12:15]
	v_mfma_f32_16x16x32_bf16 v[8:11], v[168:171], v[240:243], v[8:11]
	v_mfma_f32_16x16x32_bf16 v[52:55], v[172:175], v[212:215], v[52:55]
	v_mfma_f32_16x16x32_bf16 v[48:51], v[204:207], v[212:215], v[48:51]
	v_mfma_f32_16x16x32_bf16 v[36:39], v[172:175], v[220:223], v[36:39]
	v_mfma_f32_16x16x32_bf16 v[32:35], v[204:207], v[220:223], v[32:35]
	v_mfma_f32_16x16x32_bf16 v[20:23], v[172:175], v[228:231], v[20:23]
	v_mfma_f32_16x16x32_bf16 v[16:19], v[204:207], v[228:231], v[16:19]
	v_mfma_f32_16x16x32_bf16 v[4:7], v[172:175], v[236:239], v[4:7]
	v_mfma_f32_16x16x32_bf16 v[0:3], v[204:207], v[236:239], v[0:3]
	v_mfma_f32_16x16x32_bf16 v[52:55], v[176:179], v[216:219], v[52:55]
	v_mfma_f32_16x16x32_bf16 v[48:51], v[208:211], v[216:219], v[48:51]
	v_mfma_f32_16x16x32_bf16 v[36:39], v[176:179], v[224:227], v[36:39]
	v_mfma_f32_16x16x32_bf16 v[32:35], v[208:211], v[224:227], v[32:35]
	v_mfma_f32_16x16x32_bf16 v[20:23], v[176:179], v[232:235], v[20:23]
	v_mfma_f32_16x16x32_bf16 v[16:19], v[208:211], v[232:235], v[16:19]
	v_mfma_f32_16x16x32_bf16 v[4:7], v[176:179], v[240:243], v[4:7]
	v_mfma_f32_16x16x32_bf16 v[0:3], v[208:211], v[240:243], v[0:3]
	s_barrier
	s_add_i32 s40, s40, 2
	s_add_u32 s10, s10, 0x100
	s_addc_u32 s11, s11, 0
	s_cmp_gt_u32 s40, 13
	s_cbranch_scc0 .LBB0_997
	s_cmpk_lt_u32 s18, 0x100
	s_cbranch_scc0 .LBB0_1000
	s_barrier

.LBB0_1162:
	s_add_u32 s42, s56, 0xfffc0080
	s_addc_u32 s43, s57, -1
	s_add_i32 s60, 0, 0x10000
	s_cmp_eq_u32 s59, 4
	s_cselect_b32 s55, s15, s43
	s_cselect_b32 s54, s17, s42
	v_add_u32_e32 v140, s60, v143
	s_cselect_b32 s43, s13, s58
	s_cselect_b32 s42, s25, s53
	s_add_i32 s62, 0, 0x14000
	ds_read_b128 v[156:159], v140
	ds_read_b128 v[160:163], v140 offset:1024
	ds_read_b128 v[164:167], v140 offset:2048
	ds_read_b128 v[168:171], v140 offset:3072
	v_add_u32_e32 v140, s62, v143
	ds_read_b128 v[172:175], v140
	ds_read_b128 v[176:179], v140 offset:1024
	ds_read_b128 v[204:207], v140 offset:2048
	ds_read_b128 v[208:211], v140 offset:3072
	v_lshl_add_u64 v[140:141], s[56:57], 0, v[136:137]
	s_add_i32 m0, s23, 0xc000
	ds_read_b128 v[212:215], v154
	ds_read_b128 v[216:219], v154 offset:1024
	ds_read_b128 v[220:223], v154 offset:2048
	ds_read_b128 v[224:227], v154 offset:3072
	ds_read_b128 v[228:231], v154 offset:4096
	ds_read_b128 v[232:235], v154 offset:5120
	ds_read_b128 v[236:239], v154 offset:6144
	ds_read_b128 v[240:243], v154 offset:7168
	global_load_lds_dwordx4 v[140:141], off
	v_lshl_add_u64 v[140:141], s[56:57], 0, v[138:139]
	s_add_i32 m0, s23, 0xe000
	s_nop 0
	global_load_lds_dwordx4 v[140:141], off
	s_waitcnt vmcnt(8)
	s_waitcnt lgkmcnt(0)
	s_barrier
	s_waitcnt lgkmcnt(0)
	v_mfma_f32_16x16x32_bf16 v[124:127], v[156:159], v[212:215], v[124:127]
	v_mfma_f32_16x16x32_bf16 v[120:123], v[164:167], v[212:215], v[120:123]
	v_mfma_f32_16x16x32_bf16 v[116:119], v[156:159], v[220:223], v[116:119]
	v_mfma_f32_16x16x32_bf16 v[108:111], v[164:167], v[220:223], v[108:111]
	v_mfma_f32_16x16x32_bf16 v[100:103], v[156:159], v[228:231], v[100:103]
	v_mfma_f32_16x16x32_bf16 v[92:95], v[164:167], v[228:231], v[92:95]
	v_mfma_f32_16x16x32_bf16 v[84:87], v[156:159], v[236:239], v[84:87]
	v_mfma_f32_16x16x32_bf16 v[76:79], v[164:167], v[236:239], v[76:79]
	v_mfma_f32_16x16x32_bf16 v[124:127], v[160:163], v[216:219], v[124:127]
	v_mfma_f32_16x16x32_bf16 v[120:123], v[168:171], v[216:219], v[120:123]
	v_mfma_f32_16x16x32_bf16 v[116:119], v[160:163], v[224:227], v[116:119]
	v_mfma_f32_16x16x32_bf16 v[108:111], v[168:171], v[224:227], v[108:111]
	v_mfma_f32_16x16x32_bf16 v[100:103], v[160:163], v[232:235], v[100:103]
	v_mfma_f32_16x16x32_bf16 v[92:95], v[168:171], v[232:235], v[92:95]
	v_mfma_f32_16x16x32_bf16 v[84:87], v[160:163], v[240:243], v[84:87]
	v_mfma_f32_16x16x32_bf16 v[76:79], v[168:171], v[240:243], v[76:79]
	v_mfma_f32_16x16x32_bf16 v[112:115], v[172:175], v[212:215], v[112:115]
	v_mfma_f32_16x16x32_bf16 v[104:107], v[204:207], v[212:215], v[104:107]
	v_mfma_f32_16x16x32_bf16 v[96:99], v[172:175], v[220:223], v[96:99]
	v_mfma_f32_16x16x32_bf16 v[88:91], v[204:207], v[220:223], v[88:91]
	v_mfma_f32_16x16x32_bf16 v[80:83], v[172:175], v[228:231], v[80:83]
	v_mfma_f32_16x16x32_bf16 v[72:75], v[204:207], v[228:231], v[72:75]
	v_mfma_f32_16x16x32_bf16 v[68:71], v[172:175], v[236:239], v[68:71]
	v_mfma_f32_16x16x32_bf16 v[64:67], v[204:207], v[236:239], v[64:67]
	v_mfma_f32_16x16x32_bf16 v[112:115], v[176:179], v[216:219], v[112:115]
	v_mfma_f32_16x16x32_bf16 v[104:107], v[208:211], v[216:219], v[104:107]
	v_mfma_f32_16x16x32_bf16 v[96:99], v[176:179], v[224:227], v[96:99]
	v_mfma_f32_16x16x32_bf16 v[88:91], v[208:211], v[224:227], v[88:91]
	v_mfma_f32_16x16x32_bf16 v[80:83], v[176:179], v[232:235], v[80:83]
	v_mfma_f32_16x16x32_bf16 v[72:75], v[208:211], v[232:235], v[72:75]
	v_mfma_f32_16x16x32_bf16 v[68:71], v[176:179], v[240:243], v[68:71]
	v_mfma_f32_16x16x32_bf16 v[64:67], v[208:211], v[240:243], v[64:67]
	s_barrier
	s_add_i32 s60, s60, s36
	v_lshl_add_u64 v[140:141], s[42:43], 0, v[130:131]
	s_mov_b32 m0, s60
	ds_read_b128 v[212:215], v154 offset:16384
	ds_read_b128 v[216:219], v154 offset:17408
	ds_read_b128 v[220:223], v154 offset:18432
	ds_read_b128 v[224:227], v154 offset:19456
	ds_read_b128 v[228:231], v154 offset:20480
	ds_read_b128 v[232:235], v154 offset:21504
	ds_read_b128 v[236:239], v154 offset:22528
	ds_read_b128 v[240:243], v154 offset:23552
	global_load_lds_dwordx4 v[140:141], off
	s_add_i32 m0, s60, 0x2000
	s_add_u32 s60, s42, 0x40000
	v_lshl_add_u64 v[180:181], s[42:43], 0, v[134:135]
	s_addc_u32 s61, s43, 0
	s_add_i32 s62, s62, s36
	global_load_lds_dwordx4 v[180:181], off
	v_lshl_add_u64 v[190:191], s[60:61], 0, v[130:131]
	s_mov_b32 m0, s62
	v_lshl_add_u64 v[192:193], s[54:55], 0, v[132:133]
	global_load_lds_dwordx4 v[190:191], off
	v_lshl_add_u64 v[190:191], s[60:61], 0, v[134:135]
	s_add_i32 m0, s62, 0x2000
	s_nop 0
	global_load_lds_dwordx4 v[190:191], off
	v_lshl_add_u64 v[190:191], s[54:55], 0, v[128:129]
	s_mov_b32 m0, s23
	s_nop 0
	global_load_lds_dwordx4 v[190:191], off
	s_mov_b32 m0, s37
	s_nop 0
	global_load_lds_dwordx4 v[192:193], off
	s_waitcnt vmcnt(8)
	s_waitcnt lgkmcnt(0)
	s_barrier
	s_waitcnt lgkmcnt(0)
	v_mfma_f32_16x16x32_bf16 v[60:63], v[156:159], v[212:215], v[60:63]
	v_mfma_f32_16x16x32_bf16 v[56:59], v[164:167], v[212:215], v[56:59]
	v_mfma_f32_16x16x32_bf16 v[52:55], v[156:159], v[220:223], v[52:55]
	v_mfma_f32_16x16x32_bf16 v[44:47], v[164:167], v[220:223], v[44:47]
	v_mfma_f32_16x16x32_bf16 v[36:39], v[156:159], v[228:231], v[36:39]
	v_mfma_f32_16x16x32_bf16 v[28:31], v[164:167], v[228:231], v[28:31]
	v_mfma_f32_16x16x32_bf16 v[20:23], v[156:159], v[236:239], v[20:23]
	v_mfma_f32_16x16x32_bf16 v[12:15], v[164:167], v[236:239], v[12:15]
	v_mfma_f32_16x16x32_bf16 v[60:63], v[160:163], v[216:219], v[60:63]
	v_mfma_f32_16x16x32_bf16 v[56:59], v[168:171], v[216:219], v[56:59]
	v_mfma_f32_16x16x32_bf16 v[52:55], v[160:163], v[224:227], v[52:55]
	v_mfma_f32_16x16x32_bf16 v[44:47], v[168:171], v[224:227], v[44:47]
	v_mfma_f32_16x16x32_bf16 v[36:39], v[160:163], v[232:235], v[36:39]
	v_mfma_f32_16x16x32_bf16 v[28:31], v[168:171], v[232:235], v[28:31]
	v_mfma_f32_16x16x32_bf16 v[20:23], v[160:163], v[240:243], v[20:23]
	v_mfma_f32_16x16x32_bf16 v[12:15], v[168:171], v[240:243], v[12:15]
	v_mfma_f32_16x16x32_bf16 v[48:51], v[172:175], v[212:215], v[48:51]
	v_mfma_f32_16x16x32_bf16 v[40:43], v[204:207], v[212:215], v[40:43]
	v_mfma_f32_16x16x32_bf16 v[32:35], v[172:175], v[220:223], v[32:35]
	v_mfma_f32_16x16x32_bf16 v[24:27], v[204:207], v[220:223], v[24:27]
	v_mfma_f32_16x16x32_bf16 v[16:19], v[172:175], v[228:231], v[16:19]
	v_mfma_f32_16x16x32_bf16 v[8:11], v[204:207], v[228:231], v[8:11]
	v_mfma_f32_16x16x32_bf16 v[4:7], v[172:175], v[236:239], v[4:7]
	v_mfma_f32_16x16x32_bf16 v[0:3], v[204:207], v[236:239], v[0:3]
	v_mfma_f32_16x16x32_bf16 v[48:51], v[176:179], v[216:219], v[48:51]
	v_mfma_f32_16x16x32_bf16 v[40:43], v[208:211], v[216:219], v[40:43]
	v_mfma_f32_16x16x32_bf16 v[32:35], v[176:179], v[224:227], v[32:35]
	v_mfma_f32_16x16x32_bf16 v[24:27], v[208:211], v[224:227], v[24:27]
	v_mfma_f32_16x16x32_bf16 v[16:19], v[176:179], v[232:235], v[16:19]
	v_mfma_f32_16x16x32_bf16 v[8:11], v[208:211], v[232:235], v[8:11]
	v_mfma_f32_16x16x32_bf16 v[4:7], v[176:179], v[240:243], v[4:7]
	v_mfma_f32_16x16x32_bf16 v[0:3], v[208:211], v[240:243], v[0:3]
	s_barrier
	s_add_i32 s60, 0, 0x18000
	v_add_u32_e32 v155, s60, v143
	s_add_i32 s61, 0, 0x1c000
	ds_read_b128 v[156:159], v155
	ds_read_b128 v[160:163], v155 offset:1024
	ds_read_b128 v[164:167], v155 offset:2048
	ds_read_b128 v[168:171], v155 offset:3072
	v_add_u32_e32 v155, s61, v143
	ds_read_b128 v[172:175], v155
	ds_read_b128 v[176:179], v155 offset:1024
	ds_read_b128 v[204:207], v155 offset:2048
	ds_read_b128 v[208:211], v155 offset:3072
	s_add_u32 s54, s54, 0x40000
	s_addc_u32 s55, s55, 0
	s_mov_b32 m0, s40
	v_lshl_add_u64 v[244:245], s[54:55], 0, v[128:129]
	ds_read_b128 v[212:215], v154 offset:32768
	ds_read_b128 v[216:219], v154 offset:33792
	ds_read_b128 v[220:223], v154 offset:34816
	ds_read_b128 v[224:227], v154 offset:35840
	ds_read_b128 v[228:231], v154 offset:36864
	ds_read_b128 v[232:235], v154 offset:37888
	ds_read_b128 v[236:239], v154 offset:38912
	ds_read_b128 v[240:243], v154 offset:39936
	global_load_lds_dwordx4 v[244:245], off
	v_lshl_add_u64 v[244:245], s[54:55], 0, v[132:133]
	s_mov_b32 m0, s41
	s_nop 0
	global_load_lds_dwordx4 v[244:245], off
	s_waitcnt vmcnt(8)
	s_waitcnt lgkmcnt(0)
	s_barrier
	s_waitcnt lgkmcnt(0)
	v_mfma_f32_16x16x32_bf16 v[124:127], v[156:159], v[212:215], v[124:127]
	v_mfma_f32_16x16x32_bf16 v[120:123], v[164:167], v[212:215], v[120:123]
	v_mfma_f32_16x16x32_bf16 v[116:119], v[156:159], v[220:223], v[116:119]
	v_mfma_f32_16x16x32_bf16 v[108:111], v[164:167], v[220:223], v[108:111]
	v_mfma_f32_16x16x32_bf16 v[100:103], v[156:159], v[228:231], v[100:103]
	v_mfma_f32_16x16x32_bf16 v[92:95], v[164:167], v[228:231], v[92:95]
	v_mfma_f32_16x16x32_bf16 v[84:87], v[156:159], v[236:239], v[84:87]
	v_mfma_f32_16x16x32_bf16 v[76:79], v[164:167], v[236:239], v[76:79]
	v_mfma_f32_16x16x32_bf16 v[124:127], v[160:163], v[216:219], v[124:127]
	v_mfma_f32_16x16x32_bf16 v[120:123], v[168:171], v[216:219], v[120:123]
	v_mfma_f32_16x16x32_bf16 v[116:119], v[160:163], v[224:227], v[116:119]
	v_mfma_f32_16x16x32_bf16 v[108:111], v[168:171], v[224:227], v[108:111]
	v_mfma_f32_16x16x32_bf16 v[100:103], v[160:163], v[232:235], v[100:103]
	v_mfma_f32_16x16x32_bf16 v[92:95], v[168:171], v[232:235], v[92:95]
	v_mfma_f32_16x16x32_bf16 v[84:87], v[160:163], v[240:243], v[84:87]
	v_mfma_f32_16x16x32_bf16 v[76:79], v[168:171], v[240:243], v[76:79]
	v_mfma_f32_16x16x32_bf16 v[112:115], v[172:175], v[212:215], v[112:115]
	v_mfma_f32_16x16x32_bf16 v[104:107], v[204:207], v[212:215], v[104:107]
	v_mfma_f32_16x16x32_bf16 v[96:99], v[172:175], v[220:223], v[96:99]
	v_mfma_f32_16x16x32_bf16 v[88:91], v[204:207], v[220:223], v[88:91]
	v_mfma_f32_16x16x32_bf16 v[80:83], v[172:175], v[228:231], v[80:83]
	v_mfma_f32_16x16x32_bf16 v[72:75], v[204:207], v[228:231], v[72:75]
	v_mfma_f32_16x16x32_bf16 v[68:71], v[172:175], v[236:239], v[68:71]
	v_mfma_f32_16x16x32_bf16 v[64:67], v[204:207], v[236:239], v[64:67]
	v_mfma_f32_16x16x32_bf16 v[112:115], v[176:179], v[216:219], v[112:115]
	v_mfma_f32_16x16x32_bf16 v[104:107], v[208:211], v[216:219], v[104:107]
	v_mfma_f32_16x16x32_bf16 v[96:99], v[176:179], v[224:227], v[96:99]
	v_mfma_f32_16x16x32_bf16 v[88:91], v[208:211], v[224:227], v[88:91]
	v_mfma_f32_16x16x32_bf16 v[80:83], v[176:179], v[232:235], v[80:83]
	v_mfma_f32_16x16x32_bf16 v[72:75], v[208:211], v[232:235], v[72:75]
	v_mfma_f32_16x16x32_bf16 v[68:71], v[176:179], v[240:243], v[68:71]
	v_mfma_f32_16x16x32_bf16 v[64:67], v[208:211], v[240:243], v[64:67]
	s_barrier
	s_add_i32 s54, s60, s36
	v_lshl_add_u64 v[140:141], v[140:141], 0, s[48:49]
	s_mov_b32 m0, s54
	ds_read_b128 v[212:215], v154 offset:49152
	ds_read_b128 v[216:219], v154 offset:50176
	ds_read_b128 v[220:223], v154 offset:51200
	ds_read_b128 v[224:227], v154 offset:52224
	ds_read_b128 v[228:231], v154 offset:53248
	ds_read_b128 v[232:235], v154 offset:54272
	ds_read_b128 v[236:239], v154 offset:55296
	ds_read_b128 v[240:243], v154 offset:56320
	global_load_lds_dwordx4 v[140:141], off
	s_add_i32 m0, s54, 0x2000
	s_add_u32 s42, s42, 0x40080
	v_lshl_add_u64 v[140:141], v[180:181], 0, s[48:49]
	s_addc_u32 s43, s43, 0
	s_add_i32 s54, s61, s36
	global_load_lds_dwordx4 v[140:141], off
	v_lshl_add_u64 v[140:141], s[42:43], 0, v[130:131]
	s_mov_b32 m0, s54
	s_nop 0
	global_load_lds_dwordx4 v[140:141], off
	v_lshl_add_u64 v[140:141], s[42:43], 0, v[134:135]
	s_add_i32 m0, s54, 0x2000
	s_nop 0
	global_load_lds_dwordx4 v[140:141], off
	v_lshl_add_u64 v[140:141], v[190:191], 0, s[48:49]
	s_mov_b32 m0, s44
	s_nop 0
	global_load_lds_dwordx4 v[140:141], off
	v_lshl_add_u64 v[140:141], v[192:193], 0, s[48:49]
	s_mov_b32 m0, s45
	s_nop 0
	global_load_lds_dwordx4 v[140:141], off
	s_waitcnt vmcnt(8)
	s_waitcnt lgkmcnt(0)
	s_barrier
	s_waitcnt lgkmcnt(0)
	v_mfma_f32_16x16x32_bf16 v[60:63], v[156:159], v[212:215], v[60:63]
	v_mfma_f32_16x16x32_bf16 v[56:59], v[164:167], v[212:215], v[56:59]
	v_mfma_f32_16x16x32_bf16 v[52:55], v[156:159], v[220:223], v[52:55]
	v_mfma_f32_16x16x32_bf16 v[44:47], v[164:167], v[220:223], v[44:47]
	v_mfma_f32_16x16x32_bf16 v[36:39], v[156:159], v[228:231], v[36:39]
	v_mfma_f32_16x16x32_bf16 v[28:31], v[164:167], v[228:231], v[28:31]
	v_mfma_f32_16x16x32_bf16 v[20:23], v[156:159], v[236:239], v[20:23]
	v_mfma_f32_16x16x32_bf16 v[12:15], v[164:167], v[236:239], v[12:15]
	v_mfma_f32_16x16x32_bf16 v[60:63], v[160:163], v[216:219], v[60:63]
	v_mfma_f32_16x16x32_bf16 v[56:59], v[168:171], v[216:219], v[56:59]
	v_mfma_f32_16x16x32_bf16 v[52:55], v[160:163], v[224:227], v[52:55]
	v_mfma_f32_16x16x32_bf16 v[44:47], v[168:171], v[224:227], v[44:47]
	v_mfma_f32_16x16x32_bf16 v[36:39], v[160:163], v[232:235], v[36:39]
	v_mfma_f32_16x16x32_bf16 v[28:31], v[168:171], v[232:235], v[28:31]
	v_mfma_f32_16x16x32_bf16 v[20:23], v[160:163], v[240:243], v[20:23]
	v_mfma_f32_16x16x32_bf16 v[12:15], v[168:171], v[240:243], v[12:15]
	v_mfma_f32_16x16x32_bf16 v[48:51], v[172:175], v[212:215], v[48:51]
	v_mfma_f32_16x16x32_bf16 v[40:43], v[204:207], v[212:215], v[40:43]
	v_mfma_f32_16x16x32_bf16 v[32:35], v[172:175], v[220:223], v[32:35]
	v_mfma_f32_16x16x32_bf16 v[24:27], v[204:207], v[220:223], v[24:27]
	v_mfma_f32_16x16x32_bf16 v[16:19], v[172:175], v[228:231], v[16:19]
	v_mfma_f32_16x16x32_bf16 v[8:11], v[204:207], v[228:231], v[8:11]
	v_mfma_f32_16x16x32_bf16 v[4:7], v[172:175], v[236:239], v[4:7]
	v_mfma_f32_16x16x32_bf16 v[0:3], v[204:207], v[236:239], v[0:3]
	v_mfma_f32_16x16x32_bf16 v[48:51], v[176:179], v[216:219], v[48:51]
	v_mfma_f32_16x16x32_bf16 v[40:43], v[208:211], v[216:219], v[40:43]
	v_mfma_f32_16x16x32_bf16 v[32:35], v[176:179], v[224:227], v[32:35]
	v_mfma_f32_16x16x32_bf16 v[24:27], v[208:211], v[224:227], v[24:27]
	v_mfma_f32_16x16x32_bf16 v[16:19], v[176:179], v[232:235], v[16:19]
	v_mfma_f32_16x16x32_bf16 v[8:11], v[208:211], v[232:235], v[8:11]
	v_mfma_f32_16x16x32_bf16 v[4:7], v[176:179], v[240:243], v[4:7]
	v_mfma_f32_16x16x32_bf16 v[0:3], v[208:211], v[240:243], v[0:3]
	s_barrier
	s_add_i32 s59, s59, 2
	s_add_u32 s56, s56, 0x100
	s_addc_u32 s57, s57, 0
	s_add_u32 s53, s53, 0x100
	s_addc_u32 s58, s58, 0
	s_cmp_gt_u32 s59, 5
	s_cbranch_scc0 .LBB0_1162
	s_and_b64 vcc, exec, s[10:11]
	s_cbranch_vccz .LBB0_1165
	s_barrier
